# v58 + nt on the residual-GEMM epilogue row stores (P5/P9/P13/P17) and one final-output store group
# baseline (speedup 1.0000x reference)
.LBB0_633:
	v_lshl_or_b32 v192, s8, 8, v208
	v_lshl_add_u32 v196, s49, 8, v206
	v_ashrrev_i32_e32 v193, 31, v192
	v_ashrrev_i32_e32 v197, 31, v196
	v_lshl_add_u64 v[194:195], v[192:193], 2, s[56:57]
	v_lshlrev_b64 v[128:129], 12, v[196:197]
	v_lshl_add_u64 v[128:129], v[194:195], 0, v[128:129]
	global_load_dwordx4 v[214:217], v[128:129], off
	global_load_dwordx4 v[218:221], v[128:129], off offset:16
	global_load_dwordx4 v[222:225], v[128:129], off offset:512
	global_load_dwordx4 v[226:229], v[128:129], off offset:528
	v_or_b32_e32 v202, 16, v196
	v_or_b32_e32 v200, 32, v196
	v_or_b32_e32 v198, 48, v196
	v_ashrrev_i32_e32 v203, 31, v202
	v_ashrrev_i32_e32 v201, 31, v200
	v_ashrrev_i32_e32 v199, 31, v198
	v_lshlrev_b64 v[128:129], 12, v[202:203]
	v_lshlrev_b64 v[130:131], 12, v[200:201]
	v_lshlrev_b64 v[132:133], 12, v[198:199]
	v_lshl_add_u64 v[128:129], v[194:195], 0, v[128:129]
	v_lshl_add_u64 v[130:131], v[194:195], 0, v[130:131]
	v_lshl_add_u64 v[132:133], v[194:195], 0, v[132:133]
	global_load_dwordx4 v[168:171], v[128:129], off offset:16
	global_load_dwordx4 v[172:175], v[128:129], off
	global_load_dwordx4 v[160:163], v[128:129], off offset:528
	global_load_dwordx4 v[164:167], v[128:129], off offset:512
	global_load_dwordx4 v[152:155], v[130:131], off offset:16
	global_load_dwordx4 v[156:159], v[130:131], off
	global_load_dwordx4 v[144:147], v[130:131], off offset:528
	global_load_dwordx4 v[148:151], v[130:131], off offset:512
	global_load_dwordx4 v[136:139], v[132:133], off offset:16
	global_load_dwordx4 v[140:143], v[132:133], off
	s_nop 0
	global_load_dwordx4 v[128:131], v[132:133], off offset:528
	s_nop 0
	global_load_dwordx4 v[132:135], v[132:133], off offset:512
	v_lshlrev_b64 v[230:231], 11, v[196:197]
	v_lshl_add_u64 v[230:231], s[58:59], 0, v[230:231]
	v_lshl_add_u64 v[230:231], v[192:193], 1, v[230:231]
	s_lshl_b32 s4, s8, 2
	s_ashr_i32 s5, s4, 31
	s_waitcnt vmcnt(0)
	v_pk_add_f32 v[126:127], v[126:127], v[216:217]
	v_pk_add_f32 v[124:125], v[124:125], v[214:215]
	v_pk_add_f32 v[122:123], v[122:123], v[220:221]
	v_pk_add_f32 v[120:121], v[120:121], v[218:219]
	v_pk_add_f32 v[216:217], v[112:113], v[226:227]
	v_cvt_pk_bf16_f32 v112, v124, v125
	v_cvt_pk_bf16_f32 v113, v126, v127
	v_pk_add_f32 v[118:119], v[118:119], v[224:225]
	v_pk_add_f32 v[116:117], v[116:117], v[222:223]
	v_pk_add_f32 v[214:215], v[114:115], v[228:229]
	v_cvt_pk_bf16_f32 v114, v120, v121
	v_cvt_pk_bf16_f32 v115, v122, v123
	global_store_dwordx4 v[230:231], v[112:115], off nt
	v_lshlrev_b32_e32 v120, 16, v112
	v_lshlrev_b32_e32 v121, 16, v113
	v_and_b32_e32 v112, 0xffff0000, v112
	v_and_b32_e32 v113, 0xffff0000, v113
	v_and_b32_e32 v123, 0xffff0000, v114
	v_and_b32_e32 v125, 0xffff0000, v115
	v_lshlrev_b32_e32 v122, 16, v114
	v_lshlrev_b32_e32 v124, 16, v115
	v_cvt_pk_bf16_f32 v114, v116, v117
	v_cvt_pk_bf16_f32 v115, v118, v119
	v_cvt_pk_bf16_f32 v116, v216, v217
	v_cvt_pk_bf16_f32 v117, v214, v215
	v_mul_f32_e32 v112, v112, v112
	v_mul_f32_e32 v113, v113, v113
	v_mul_f32_e32 v118, v123, v123
	v_mul_f32_e32 v119, v125, v125
	v_and_b32_e32 v125, 0xffff0000, v114
	v_and_b32_e32 v127, 0xffff0000, v115
	v_and_b32_e32 v214, 0xffff0000, v116
	v_and_b32_e32 v216, 0xffff0000, v117
	v_lshlrev_b32_e32 v123, 16, v114
	v_lshlrev_b32_e32 v126, 16, v115
	v_lshlrev_b32_e32 v213, 16, v116
	v_lshlrev_b32_e32 v215, 16, v117
	v_fmac_f32_e32 v112, v120, v120
	v_fmac_f32_e32 v113, v121, v121
	v_fmac_f32_e32 v118, v122, v122
	v_fmac_f32_e32 v119, v124, v124
	v_mul_f32_e32 v120, v125, v125
	v_mul_f32_e32 v121, v127, v127
	v_mul_f32_e32 v122, v214, v214
	v_mul_f32_e32 v124, v216, v216
	v_add_f32_e32 v112, v112, v113
	v_add_f32_e32 v113, v118, v119
	v_fmac_f32_e32 v120, v123, v123
	v_fmac_f32_e32 v121, v126, v126
	v_fmac_f32_e32 v122, v213, v213
	v_fmac_f32_e32 v124, v215, v215
	v_add_f32_e32 v112, v112, v113
	v_add_f32_e32 v113, v120, v121
	v_add_f32_e32 v118, v122, v124
	v_add_f32_e32 v113, v113, v118
	v_and_b32_e32 v118, 64, v212
	v_add_f32_e32 v112, v112, v113
	v_xor_b32_e32 v113, 16, v212
	v_add_u32_e32 v118, 64, v118
	v_cmp_lt_i32_e32 vcc, v113, v118
	global_store_dwordx4 v[230:231], v[114:117], off offset:256 nt
	s_nop 0
	v_cndmask_b32_e32 v113, v212, v113, vcc
	v_lshlrev_b32_e32 v120, 2, v113
	ds_bpermute_b32 v113, v120, v112
	s_waitcnt lgkmcnt(0)
	v_add_f32_e32 v112, v112, v113
	v_xor_b32_e32 v113, 32, v212
	v_cmp_lt_i32_e32 vcc, v113, v118
	s_nop 1
	v_cndmask_b32_e32 v113, v212, v113, vcc
	v_lshlrev_b32_e32 v121, 2, v113
	ds_bpermute_b32 v113, v121, v112
	s_and_saveexec_b64 s[24:25], s[0:1]
	s_cbranch_execz .LBB0_635
	v_lshlrev_b64 v[114:115], 6, v[196:197]
	v_lshl_add_u64 v[114:115], s[62:63], 0, v[114:115]
	v_lshl_add_u64 v[114:115], s[4:5], 2, v[114:115]
	s_lshl_b32 s8, s41, 2
	v_lshl_add_u64 v[114:115], v[114:115], 0, s[8:9]
	s_waitcnt lgkmcnt(0)
	v_add_f32_e32 v112, v112, v113
	global_store_dword v[114:115], v112, off
.LBB0_635:
	s_or_b64 exec, exec, s[24:25]
	s_waitcnt lgkmcnt(0)
	v_lshlrev_b64 v[112:113], 10, v[202:203]
	v_pk_add_f32 v[108:109], v[108:109], v[172:173]
	v_pk_add_f32 v[114:115], v[106:107], v[170:171]
	v_pk_add_f32 v[106:107], v[104:105], v[168:169]
	v_cvt_pk_bf16_f32 v104, v108, v109
	v_lshl_add_u64 v[108:109], v[112:113], 1, s[58:59]
	v_pk_add_f32 v[110:111], v[110:111], v[174:175]
	v_lshl_add_u64 v[108:109], v[192:193], 1, v[108:109]
	v_cvt_pk_bf16_f32 v105, v110, v111
	v_cvt_pk_bf16_f32 v106, v106, v107
	v_cvt_pk_bf16_f32 v107, v114, v115
	global_store_dwordx4 v[108:109], v[104:107], off nt
	v_lshlrev_b32_e32 v110, 16, v104
	v_lshlrev_b32_e32 v111, 16, v105
	v_and_b32_e32 v104, 0xffff0000, v104
	v_and_b32_e32 v105, 0xffff0000, v105
	v_mul_f32_e32 v104, v104, v104
	v_mul_f32_e32 v105, v105, v105
	v_lshlrev_b32_e32 v112, 16, v106
	v_and_b32_e32 v106, 0xffff0000, v106
	v_lshlrev_b32_e32 v113, 16, v107
	v_and_b32_e32 v107, 0xffff0000, v107
	v_fmac_f32_e32 v104, v110, v110
	v_fmac_f32_e32 v105, v111, v111
	v_add_f32_e32 v104, v104, v105
	v_mul_f32_e32 v105, v106, v106
	v_mul_f32_e32 v106, v107, v107
	v_fmac_f32_e32 v105, v112, v112
	v_fmac_f32_e32 v106, v113, v113
	v_add_f32_e32 v105, v105, v106
	v_pk_add_f32 v[100:101], v[100:101], v[164:165]
	v_pk_add_f32 v[96:97], v[96:97], v[160:161]
	v_add_f32_e32 v106, v104, v105
	v_pk_add_f32 v[102:103], v[102:103], v[166:167]
	v_pk_add_f32 v[104:105], v[98:99], v[162:163]
	v_cvt_pk_bf16_f32 v98, v100, v101
	v_cvt_pk_bf16_f32 v99, v102, v103
	v_cvt_pk_bf16_f32 v100, v96, v97
	s_nop 0
	v_and_b32_e32 v97, 0xffff0000, v98
	v_lshlrev_b32_e32 v96, 16, v98
	v_and_b32_e32 v103, 0xffff0000, v99
	v_mul_f32_e32 v97, v97, v97
	v_lshlrev_b32_e32 v102, 16, v99
	v_fmac_f32_e32 v97, v96, v96
	v_mul_f32_e32 v96, v103, v103
	v_cvt_pk_bf16_f32 v101, v104, v105
	v_and_b32_e32 v105, 0xffff0000, v100
	v_and_b32_e32 v110, 0xffff0000, v101
	v_fmac_f32_e32 v96, v102, v102
	v_lshlrev_b32_e32 v104, 16, v100
	v_lshlrev_b32_e32 v107, 16, v101
	v_add_f32_e32 v96, v97, v96
	v_mul_f32_e32 v97, v105, v105
	v_mul_f32_e32 v102, v110, v110
	v_fmac_f32_e32 v97, v104, v104
	v_fmac_f32_e32 v102, v107, v107
	v_add_f32_e32 v97, v97, v102
	v_add_f32_e32 v96, v96, v97
	v_add_f32_e32 v96, v106, v96
	ds_bpermute_b32 v97, v120, v96
	global_store_dwordx4 v[108:109], v[98:101], off offset:256 nt
	s_waitcnt lgkmcnt(0)
	v_add_f32_e32 v96, v96, v97
	ds_bpermute_b32 v97, v121, v96
	s_and_saveexec_b64 s[24:25], s[0:1]
	s_cbranch_execz .LBB0_637
	v_lshlrev_b64 v[98:99], 6, v[202:203]
	v_lshl_add_u64 v[98:99], s[62:63], 0, v[98:99]
	v_lshl_add_u64 v[98:99], s[4:5], 2, v[98:99]
	s_lshl_b32 s8, s41, 2
	v_lshl_add_u64 v[98:99], v[98:99], 0, s[8:9]
	s_waitcnt lgkmcnt(0)
	v_add_f32_e32 v96, v96, v97
	global_store_dword v[98:99], v96, off
.LBB0_637:
	s_or_b64 exec, exec, s[24:25]
	s_waitcnt lgkmcnt(0)
	v_lshlrev_b64 v[96:97], 10, v[200:201]
	v_pk_add_f32 v[92:93], v[92:93], v[156:157]
	v_pk_add_f32 v[98:99], v[90:91], v[154:155]
	v_pk_add_f32 v[90:91], v[88:89], v[152:153]
	v_cvt_pk_bf16_f32 v88, v92, v93
	v_lshl_add_u64 v[92:93], v[96:97], 1, s[58:59]
	v_pk_add_f32 v[94:95], v[94:95], v[158:159]
	v_lshl_add_u64 v[92:93], v[192:193], 1, v[92:93]
	v_cvt_pk_bf16_f32 v89, v94, v95
	v_cvt_pk_bf16_f32 v90, v90, v91
	v_cvt_pk_bf16_f32 v91, v98, v99
	global_store_dwordx4 v[92:93], v[88:91], off nt
	v_lshlrev_b32_e32 v94, 16, v88
	v_lshlrev_b32_e32 v95, 16, v89
	v_and_b32_e32 v88, 0xffff0000, v88
	v_and_b32_e32 v89, 0xffff0000, v89
	v_mul_f32_e32 v88, v88, v88
	v_mul_f32_e32 v89, v89, v89
	v_lshlrev_b32_e32 v96, 16, v90
	v_and_b32_e32 v90, 0xffff0000, v90
	v_lshlrev_b32_e32 v97, 16, v91
	v_and_b32_e32 v91, 0xffff0000, v91
	v_fmac_f32_e32 v88, v94, v94
	v_fmac_f32_e32 v89, v95, v95
	v_add_f32_e32 v88, v88, v89
	v_mul_f32_e32 v89, v90, v90
	v_mul_f32_e32 v90, v91, v91
	v_fmac_f32_e32 v89, v96, v96
	v_fmac_f32_e32 v90, v97, v97
	v_add_f32_e32 v89, v89, v90
	v_pk_add_f32 v[84:85], v[84:85], v[148:149]
	v_pk_add_f32 v[80:81], v[80:81], v[144:145]
	v_add_f32_e32 v90, v88, v89
	v_pk_add_f32 v[86:87], v[86:87], v[150:151]
	v_pk_add_f32 v[88:89], v[82:83], v[146:147]
	v_cvt_pk_bf16_f32 v82, v84, v85
	v_cvt_pk_bf16_f32 v83, v86, v87
	v_cvt_pk_bf16_f32 v84, v80, v81
	s_nop 0
	v_and_b32_e32 v81, 0xffff0000, v82
	v_lshlrev_b32_e32 v80, 16, v82
	v_and_b32_e32 v87, 0xffff0000, v83
	v_mul_f32_e32 v81, v81, v81
	v_lshlrev_b32_e32 v86, 16, v83
	v_fmac_f32_e32 v81, v80, v80
	v_mul_f32_e32 v80, v87, v87
	v_cvt_pk_bf16_f32 v85, v88, v89
	v_and_b32_e32 v89, 0xffff0000, v84
	v_and_b32_e32 v94, 0xffff0000, v85
	v_fmac_f32_e32 v80, v86, v86
	v_lshlrev_b32_e32 v88, 16, v84
	v_lshlrev_b32_e32 v91, 16, v85
	v_add_f32_e32 v80, v81, v80
	v_mul_f32_e32 v81, v89, v89
	v_mul_f32_e32 v86, v94, v94
	v_fmac_f32_e32 v81, v88, v88
	v_fmac_f32_e32 v86, v91, v91
	v_add_f32_e32 v81, v81, v86
	v_add_f32_e32 v80, v80, v81
	v_add_f32_e32 v80, v90, v80
	ds_bpermute_b32 v81, v120, v80
	global_store_dwordx4 v[92:93], v[82:85], off offset:256 nt
	s_waitcnt lgkmcnt(0)
	v_add_f32_e32 v80, v80, v81
	ds_bpermute_b32 v81, v121, v80
	s_and_saveexec_b64 s[24:25], s[0:1]
	s_cbranch_execz .LBB0_639
	v_lshlrev_b64 v[82:83], 6, v[200:201]
	v_lshl_add_u64 v[82:83], s[62:63], 0, v[82:83]
	v_lshl_add_u64 v[82:83], s[4:5], 2, v[82:83]
	s_lshl_b32 s8, s41, 2
	v_lshl_add_u64 v[82:83], v[82:83], 0, s[8:9]
	s_waitcnt lgkmcnt(0)
	v_add_f32_e32 v80, v80, v81
	global_store_dword v[82:83], v80, off
.LBB0_639:
	s_or_b64 exec, exec, s[24:25]
	s_waitcnt lgkmcnt(0)
	v_lshlrev_b64 v[80:81], 10, v[198:199]
	v_pk_add_f32 v[76:77], v[76:77], v[140:141]
	v_pk_add_f32 v[82:83], v[74:75], v[138:139]
	v_pk_add_f32 v[74:75], v[72:73], v[136:137]
	v_cvt_pk_bf16_f32 v72, v76, v77
	v_lshl_add_u64 v[76:77], v[80:81], 1, s[58:59]
	v_pk_add_f32 v[78:79], v[78:79], v[142:143]
	v_lshl_add_u64 v[76:77], v[192:193], 1, v[76:77]
	v_cvt_pk_bf16_f32 v73, v78, v79
	v_cvt_pk_bf16_f32 v74, v74, v75
	v_cvt_pk_bf16_f32 v75, v82, v83
	global_store_dwordx4 v[76:77], v[72:75], off nt
	v_lshlrev_b32_e32 v78, 16, v72
	v_lshlrev_b32_e32 v79, 16, v73
	v_and_b32_e32 v72, 0xffff0000, v72
	v_and_b32_e32 v73, 0xffff0000, v73
	v_mul_f32_e32 v72, v72, v72
	v_mul_f32_e32 v73, v73, v73
	v_lshlrev_b32_e32 v80, 16, v74
	v_and_b32_e32 v74, 0xffff0000, v74
	v_lshlrev_b32_e32 v81, 16, v75
	v_and_b32_e32 v75, 0xffff0000, v75
	v_fmac_f32_e32 v72, v78, v78
	v_fmac_f32_e32 v73, v79, v79
	v_add_f32_e32 v72, v72, v73
	v_mul_f32_e32 v73, v74, v74
	v_mul_f32_e32 v74, v75, v75
	v_fmac_f32_e32 v73, v80, v80
	v_fmac_f32_e32 v74, v81, v81
	v_add_f32_e32 v73, v73, v74
	v_pk_add_f32 v[68:69], v[68:69], v[132:133]
	v_pk_add_f32 v[64:65], v[64:65], v[128:129]
	v_add_f32_e32 v74, v72, v73
	v_pk_add_f32 v[70:71], v[70:71], v[134:135]
	v_pk_add_f32 v[72:73], v[66:67], v[130:131]
	v_cvt_pk_bf16_f32 v66, v68, v69
	v_cvt_pk_bf16_f32 v67, v70, v71
	v_cvt_pk_bf16_f32 v68, v64, v65
	s_nop 0
	v_and_b32_e32 v65, 0xffff0000, v66
	v_lshlrev_b32_e32 v64, 16, v66
	v_and_b32_e32 v71, 0xffff0000, v67
	v_mul_f32_e32 v65, v65, v65
	v_lshlrev_b32_e32 v70, 16, v67
	v_fmac_f32_e32 v65, v64, v64
	v_mul_f32_e32 v64, v71, v71
	v_cvt_pk_bf16_f32 v69, v72, v73
	v_and_b32_e32 v73, 0xffff0000, v68
	v_and_b32_e32 v78, 0xffff0000, v69
	v_fmac_f32_e32 v64, v70, v70
	v_lshlrev_b32_e32 v72, 16, v68
	v_lshlrev_b32_e32 v75, 16, v69
	v_add_f32_e32 v64, v65, v64
	v_mul_f32_e32 v65, v73, v73
	v_mul_f32_e32 v70, v78, v78
	v_fmac_f32_e32 v65, v72, v72
	v_fmac_f32_e32 v70, v75, v75
	v_add_f32_e32 v65, v65, v70
	v_add_f32_e32 v64, v64, v65
	v_add_f32_e32 v64, v74, v64
	ds_bpermute_b32 v65, v120, v64
	global_store_dwordx4 v[76:77], v[66:69], off offset:256 nt
	s_waitcnt lgkmcnt(0)
	v_add_f32_e32 v64, v64, v65
	ds_bpermute_b32 v65, v121, v64
	s_and_saveexec_b64 s[24:25], s[0:1]
	s_cbranch_execz .LBB0_641
	v_lshlrev_b64 v[66:67], 6, v[198:199]
	v_lshl_add_u64 v[66:67], s[62:63], 0, v[66:67]
	v_lshl_add_u64 v[66:67], s[4:5], 2, v[66:67]
	s_lshl_b32 s8, s41, 2
	v_lshl_add_u64 v[66:67], v[66:67], 0, s[8:9]
	s_waitcnt lgkmcnt(0)
	v_add_f32_e32 v64, v64, v65
	global_store_dword v[66:67], v64, off
.LBB0_641:
	s_or_b64 exec, exec, s[24:25]
	v_add_u32_e32 v118, 0x80, v196
	v_ashrrev_i32_e32 v119, 31, v118
	s_waitcnt lgkmcnt(0)
	v_lshlrev_b64 v[64:65], 12, v[118:119]
	v_lshl_add_u64 v[64:65], v[194:195], 0, v[64:65]
	global_load_dwordx4 v[122:125], v[64:65], off
	global_load_dwordx4 v[126:129], v[64:65], off offset:16
	global_load_dwordx4 v[130:133], v[64:65], off offset:512
	global_load_dwordx4 v[134:137], v[64:65], off offset:528
	v_add_u32_e32 v116, 0x90, v196
	v_add_u32_e32 v114, 0xa0, v196
	v_add_u32_e32 v112, 0xb0, v196
	v_ashrrev_i32_e32 v117, 31, v116
	v_ashrrev_i32_e32 v115, 31, v114
	v_ashrrev_i32_e32 v113, 31, v112
	v_lshlrev_b64 v[64:65], 12, v[116:117]
	v_lshlrev_b64 v[66:67], 12, v[114:115]
	v_lshlrev_b64 v[68:69], 12, v[112:113]
	v_lshl_add_u64 v[64:65], v[194:195], 0, v[64:65]
	v_lshl_add_u64 v[66:67], v[194:195], 0, v[66:67]
	v_lshl_add_u64 v[68:69], v[194:195], 0, v[68:69]
	global_load_dwordx4 v[104:107], v[64:65], off offset:16
	global_load_dwordx4 v[108:111], v[64:65], off
	global_load_dwordx4 v[96:99], v[64:65], off offset:528
	global_load_dwordx4 v[100:103], v[64:65], off offset:512
	global_load_dwordx4 v[88:91], v[66:67], off offset:16
	global_load_dwordx4 v[92:95], v[66:67], off
	global_load_dwordx4 v[80:83], v[66:67], off offset:528
	global_load_dwordx4 v[84:87], v[66:67], off offset:512
	global_load_dwordx4 v[72:75], v[68:69], off offset:16
	global_load_dwordx4 v[76:79], v[68:69], off
	s_nop 0
	global_load_dwordx4 v[64:67], v[68:69], off offset:528
	s_nop 0
	global_load_dwordx4 v[68:71], v[68:69], off offset:512
	v_lshlrev_b64 v[138:139], 11, v[118:119]
	v_lshl_add_u64 v[138:139], s[58:59], 0, v[138:139]
	v_lshl_add_u64 v[138:139], v[192:193], 1, v[138:139]
	s_waitcnt vmcnt(15)
	v_pk_add_f32 v[62:63], v[62:63], v[124:125]
	v_pk_add_f32 v[60:61], v[60:61], v[122:123]
	s_waitcnt vmcnt(14)
	v_pk_add_f32 v[58:59], v[58:59], v[128:129]
	v_pk_add_f32 v[56:57], v[56:57], v[126:127]
	s_waitcnt vmcnt(12)
	v_pk_add_f32 v[124:125], v[48:49], v[134:135]
	v_cvt_pk_bf16_f32 v48, v60, v61
	v_cvt_pk_bf16_f32 v49, v62, v63
	v_pk_add_f32 v[54:55], v[54:55], v[132:133]
	v_pk_add_f32 v[52:53], v[52:53], v[130:131]
	v_pk_add_f32 v[122:123], v[50:51], v[136:137]
	v_cvt_pk_bf16_f32 v50, v56, v57
	v_cvt_pk_bf16_f32 v51, v58, v59
	global_store_dwordx4 v[138:139], v[48:51], off nt
	v_lshlrev_b32_e32 v56, 16, v48
	v_lshlrev_b32_e32 v57, 16, v49
	v_and_b32_e32 v48, 0xffff0000, v48
	v_and_b32_e32 v49, 0xffff0000, v49
	v_and_b32_e32 v59, 0xffff0000, v50
	v_and_b32_e32 v61, 0xffff0000, v51
	v_lshlrev_b32_e32 v58, 16, v50
	v_lshlrev_b32_e32 v60, 16, v51
	v_cvt_pk_bf16_f32 v50, v52, v53
	v_cvt_pk_bf16_f32 v51, v54, v55
	v_cvt_pk_bf16_f32 v52, v124, v125
	v_cvt_pk_bf16_f32 v53, v122, v123
	v_mul_f32_e32 v48, v48, v48
	v_mul_f32_e32 v49, v49, v49
	v_mul_f32_e32 v54, v59, v59
	v_mul_f32_e32 v55, v61, v61
	v_and_b32_e32 v61, 0xffff0000, v50
	v_and_b32_e32 v63, 0xffff0000, v51
	v_and_b32_e32 v123, 0xffff0000, v52
	v_and_b32_e32 v125, 0xffff0000, v53
	v_lshlrev_b32_e32 v59, 16, v50
	v_lshlrev_b32_e32 v62, 16, v51
	v_lshlrev_b32_e32 v122, 16, v52
	v_lshlrev_b32_e32 v124, 16, v53
	v_fmac_f32_e32 v48, v56, v56
	v_fmac_f32_e32 v49, v57, v57
	v_fmac_f32_e32 v54, v58, v58
	v_fmac_f32_e32 v55, v60, v60
	v_mul_f32_e32 v56, v61, v61
	v_mul_f32_e32 v57, v63, v63
	v_mul_f32_e32 v58, v123, v123
	v_mul_f32_e32 v60, v125, v125
	v_add_f32_e32 v48, v48, v49
	v_add_f32_e32 v49, v54, v55
	v_fmac_f32_e32 v56, v59, v59
	v_fmac_f32_e32 v57, v62, v62
	v_fmac_f32_e32 v58, v122, v122
	v_fmac_f32_e32 v60, v124, v124
	v_add_f32_e32 v48, v48, v49
	v_add_f32_e32 v49, v56, v57
	v_add_f32_e32 v54, v58, v60
	v_add_f32_e32 v49, v49, v54
	v_add_f32_e32 v48, v48, v49
	ds_bpermute_b32 v49, v120, v48
	global_store_dwordx4 v[138:139], v[50:53], off offset:256 nt
	s_waitcnt lgkmcnt(0)
	v_add_f32_e32 v48, v48, v49
	ds_bpermute_b32 v49, v121, v48
	s_and_saveexec_b64 s[24:25], s[0:1]
	s_cbranch_execz .LBB0_643
	v_lshlrev_b64 v[50:51], 6, v[118:119]
	v_lshl_add_u64 v[50:51], s[62:63], 0, v[50:51]
	v_lshl_add_u64 v[50:51], s[4:5], 2, v[50:51]
	s_lshl_b32 s8, s41, 2
	v_lshl_add_u64 v[50:51], v[50:51], 0, s[8:9]
	s_waitcnt lgkmcnt(0)
	v_add_f32_e32 v48, v48, v49
	global_store_dword v[50:51], v48, off
.LBB0_643:
	s_or_b64 exec, exec, s[24:25]
	s_waitcnt lgkmcnt(0)
	v_lshlrev_b64 v[48:49], 10, v[116:117]
	s_waitcnt vmcnt(12)
	v_pk_add_f32 v[44:45], v[44:45], v[108:109]
	v_pk_add_f32 v[50:51], v[42:43], v[106:107]
	v_pk_add_f32 v[42:43], v[40:41], v[104:105]
	v_cvt_pk_bf16_f32 v40, v44, v45
	v_lshl_add_u64 v[44:45], v[48:49], 1, s[58:59]
	v_pk_add_f32 v[46:47], v[46:47], v[110:111]
	v_lshl_add_u64 v[44:45], v[192:193], 1, v[44:45]
	v_cvt_pk_bf16_f32 v41, v46, v47
	v_cvt_pk_bf16_f32 v42, v42, v43
	v_cvt_pk_bf16_f32 v43, v50, v51
	global_store_dwordx4 v[44:45], v[40:43], off nt
	v_lshlrev_b32_e32 v46, 16, v40
	v_lshlrev_b32_e32 v47, 16, v41
	v_and_b32_e32 v40, 0xffff0000, v40
	v_and_b32_e32 v41, 0xffff0000, v41
	v_mul_f32_e32 v40, v40, v40
	v_mul_f32_e32 v41, v41, v41
	v_lshlrev_b32_e32 v48, 16, v42
	v_and_b32_e32 v42, 0xffff0000, v42
	v_lshlrev_b32_e32 v49, 16, v43
	v_and_b32_e32 v43, 0xffff0000, v43
	v_fmac_f32_e32 v40, v46, v46
	v_fmac_f32_e32 v41, v47, v47
	v_add_f32_e32 v40, v40, v41
	v_mul_f32_e32 v41, v42, v42
	v_mul_f32_e32 v42, v43, v43
	v_fmac_f32_e32 v41, v48, v48
	v_fmac_f32_e32 v42, v49, v49
	v_add_f32_e32 v41, v41, v42
	s_waitcnt vmcnt(11)
	v_pk_add_f32 v[36:37], v[36:37], v[100:101]
	v_pk_add_f32 v[32:33], v[32:33], v[96:97]
	v_add_f32_e32 v42, v40, v41
	v_pk_add_f32 v[38:39], v[38:39], v[102:103]
	v_pk_add_f32 v[40:41], v[34:35], v[98:99]
	v_cvt_pk_bf16_f32 v34, v36, v37
	v_cvt_pk_bf16_f32 v35, v38, v39
	v_cvt_pk_bf16_f32 v36, v32, v33
	s_nop 0
	v_and_b32_e32 v33, 0xffff0000, v34
	v_lshlrev_b32_e32 v32, 16, v34
	v_and_b32_e32 v39, 0xffff0000, v35
	v_mul_f32_e32 v33, v33, v33
	v_lshlrev_b32_e32 v38, 16, v35
	v_fmac_f32_e32 v33, v32, v32
	v_mul_f32_e32 v32, v39, v39
	v_cvt_pk_bf16_f32 v37, v40, v41
	v_and_b32_e32 v41, 0xffff0000, v36
	v_and_b32_e32 v46, 0xffff0000, v37
	v_fmac_f32_e32 v32, v38, v38
	v_lshlrev_b32_e32 v40, 16, v36
	v_lshlrev_b32_e32 v43, 16, v37
	v_add_f32_e32 v32, v33, v32
	v_mul_f32_e32 v33, v41, v41
	v_mul_f32_e32 v38, v46, v46
	v_fmac_f32_e32 v33, v40, v40
	v_fmac_f32_e32 v38, v43, v43
	v_add_f32_e32 v33, v33, v38
	v_add_f32_e32 v32, v32, v33
	v_add_f32_e32 v32, v42, v32
	ds_bpermute_b32 v33, v120, v32
	global_store_dwordx4 v[44:45], v[34:37], off offset:256 nt
	s_waitcnt lgkmcnt(0)
	v_add_f32_e32 v32, v32, v33
	ds_bpermute_b32 v33, v121, v32
	s_and_saveexec_b64 s[24:25], s[0:1]
	s_cbranch_execz .LBB0_645
	v_lshlrev_b64 v[34:35], 6, v[116:117]
	v_lshl_add_u64 v[34:35], s[62:63], 0, v[34:35]
	v_lshl_add_u64 v[34:35], s[4:5], 2, v[34:35]
	s_lshl_b32 s8, s41, 2
	v_lshl_add_u64 v[34:35], v[34:35], 0, s[8:9]
	s_waitcnt lgkmcnt(0)
	v_add_f32_e32 v32, v32, v33
	global_store_dword v[34:35], v32, off
.LBB0_645:
	s_or_b64 exec, exec, s[24:25]
	s_waitcnt lgkmcnt(0)
	v_lshlrev_b64 v[32:33], 10, v[114:115]
	s_waitcnt vmcnt(10)
	v_pk_add_f32 v[28:29], v[28:29], v[92:93]
	v_pk_add_f32 v[34:35], v[26:27], v[90:91]
	v_pk_add_f32 v[26:27], v[24:25], v[88:89]
	v_cvt_pk_bf16_f32 v24, v28, v29
	v_lshl_add_u64 v[28:29], v[32:33], 1, s[58:59]
	v_pk_add_f32 v[30:31], v[30:31], v[94:95]
	v_lshl_add_u64 v[28:29], v[192:193], 1, v[28:29]
	v_cvt_pk_bf16_f32 v25, v30, v31
	v_cvt_pk_bf16_f32 v26, v26, v27
	v_cvt_pk_bf16_f32 v27, v34, v35
	global_store_dwordx4 v[28:29], v[24:27], off nt
	v_lshlrev_b32_e32 v30, 16, v24
	v_lshlrev_b32_e32 v31, 16, v25
	v_and_b32_e32 v24, 0xffff0000, v24
	v_and_b32_e32 v25, 0xffff0000, v25
	v_mul_f32_e32 v24, v24, v24
	v_mul_f32_e32 v25, v25, v25
	v_lshlrev_b32_e32 v32, 16, v26
	v_and_b32_e32 v26, 0xffff0000, v26
	v_lshlrev_b32_e32 v33, 16, v27
	v_and_b32_e32 v27, 0xffff0000, v27
	v_fmac_f32_e32 v24, v30, v30
	v_fmac_f32_e32 v25, v31, v31
	v_add_f32_e32 v24, v24, v25
	v_mul_f32_e32 v25, v26, v26
	v_mul_f32_e32 v26, v27, v27
	v_fmac_f32_e32 v25, v32, v32
	v_fmac_f32_e32 v26, v33, v33
	v_add_f32_e32 v25, v25, v26
	s_waitcnt vmcnt(9)
	v_pk_add_f32 v[20:21], v[20:21], v[84:85]
	v_pk_add_f32 v[16:17], v[16:17], v[80:81]
	v_add_f32_e32 v26, v24, v25
	v_pk_add_f32 v[22:23], v[22:23], v[86:87]
	v_pk_add_f32 v[24:25], v[18:19], v[82:83]
	v_cvt_pk_bf16_f32 v18, v20, v21
	v_cvt_pk_bf16_f32 v19, v22, v23
	v_cvt_pk_bf16_f32 v20, v16, v17
	s_nop 0
	v_and_b32_e32 v17, 0xffff0000, v18
	v_lshlrev_b32_e32 v16, 16, v18
	v_and_b32_e32 v23, 0xffff0000, v19
	v_mul_f32_e32 v17, v17, v17
	v_lshlrev_b32_e32 v22, 16, v19
	v_fmac_f32_e32 v17, v16, v16
	v_mul_f32_e32 v16, v23, v23
	v_cvt_pk_bf16_f32 v21, v24, v25
	v_and_b32_e32 v25, 0xffff0000, v20
	v_and_b32_e32 v30, 0xffff0000, v21
	v_fmac_f32_e32 v16, v22, v22
	v_lshlrev_b32_e32 v24, 16, v20
	v_lshlrev_b32_e32 v27, 16, v21
	v_add_f32_e32 v16, v17, v16
	v_mul_f32_e32 v17, v25, v25
	v_mul_f32_e32 v22, v30, v30
	v_fmac_f32_e32 v17, v24, v24
	v_fmac_f32_e32 v22, v27, v27
	v_add_f32_e32 v17, v17, v22
	v_add_f32_e32 v16, v16, v17
	v_add_f32_e32 v16, v26, v16
	ds_bpermute_b32 v17, v120, v16
	global_store_dwordx4 v[28:29], v[18:21], off offset:256 nt
	s_waitcnt lgkmcnt(0)
	v_add_f32_e32 v16, v16, v17
	ds_bpermute_b32 v17, v121, v16
	s_and_saveexec_b64 s[24:25], s[0:1]
	s_cbranch_execz .LBB0_647
	v_lshlrev_b64 v[18:19], 6, v[114:115]
	v_lshl_add_u64 v[18:19], s[62:63], 0, v[18:19]
	v_lshl_add_u64 v[18:19], s[4:5], 2, v[18:19]
	s_lshl_b32 s8, s41, 2
	v_lshl_add_u64 v[18:19], v[18:19], 0, s[8:9]
	s_waitcnt lgkmcnt(0)
	v_add_f32_e32 v16, v16, v17
	global_store_dword v[18:19], v16, off
.LBB0_647:
	s_or_b64 exec, exec, s[24:25]
	s_waitcnt lgkmcnt(0)
	v_lshlrev_b64 v[16:17], 10, v[112:113]
	s_waitcnt vmcnt(8)
	v_pk_add_f32 v[12:13], v[12:13], v[76:77]
	v_pk_add_f32 v[18:19], v[10:11], v[74:75]
	v_pk_add_f32 v[10:11], v[8:9], v[72:73]
	v_cvt_pk_bf16_f32 v8, v12, v13
	v_lshl_add_u64 v[12:13], v[16:17], 1, s[58:59]
	v_pk_add_f32 v[14:15], v[14:15], v[78:79]
	v_lshl_add_u64 v[12:13], v[192:193], 1, v[12:13]
	v_cvt_pk_bf16_f32 v9, v14, v15
	v_cvt_pk_bf16_f32 v10, v10, v11
	v_cvt_pk_bf16_f32 v11, v18, v19
	global_store_dwordx4 v[12:13], v[8:11], off nt
	v_lshlrev_b32_e32 v14, 16, v8
	v_lshlrev_b32_e32 v15, 16, v9
	v_and_b32_e32 v8, 0xffff0000, v8
	v_and_b32_e32 v9, 0xffff0000, v9
	v_mul_f32_e32 v8, v8, v8
	v_mul_f32_e32 v9, v9, v9
	v_lshlrev_b32_e32 v16, 16, v10
	v_and_b32_e32 v10, 0xffff0000, v10
	v_lshlrev_b32_e32 v17, 16, v11
	v_and_b32_e32 v11, 0xffff0000, v11
	v_fmac_f32_e32 v8, v14, v14
	v_fmac_f32_e32 v9, v15, v15
	v_add_f32_e32 v8, v8, v9
	v_mul_f32_e32 v9, v10, v10
	v_mul_f32_e32 v10, v11, v11
	v_fmac_f32_e32 v9, v16, v16
	v_fmac_f32_e32 v10, v17, v17
	v_add_f32_e32 v9, v9, v10
	s_waitcnt vmcnt(7)
	v_pk_add_f32 v[4:5], v[4:5], v[68:69]
	v_pk_add_f32 v[0:1], v[0:1], v[64:65]
	v_add_f32_e32 v10, v8, v9
	v_pk_add_f32 v[6:7], v[6:7], v[70:71]
	v_pk_add_f32 v[8:9], v[2:3], v[66:67]
	v_cvt_pk_bf16_f32 v2, v4, v5
	v_cvt_pk_bf16_f32 v3, v6, v7
	v_cvt_pk_bf16_f32 v4, v0, v1
	s_nop 0
	v_and_b32_e32 v1, 0xffff0000, v2
	v_lshlrev_b32_e32 v0, 16, v2
	v_and_b32_e32 v7, 0xffff0000, v3
	v_mul_f32_e32 v1, v1, v1
	v_lshlrev_b32_e32 v6, 16, v3
	v_fmac_f32_e32 v1, v0, v0
	v_mul_f32_e32 v0, v7, v7
	v_cvt_pk_bf16_f32 v5, v8, v9
	v_and_b32_e32 v9, 0xffff0000, v4
	v_and_b32_e32 v14, 0xffff0000, v5
	v_fmac_f32_e32 v0, v6, v6
	v_lshlrev_b32_e32 v8, 16, v4
	v_lshlrev_b32_e32 v11, 16, v5
	v_add_f32_e32 v0, v1, v0
	v_mul_f32_e32 v1, v9, v9
	v_mul_f32_e32 v6, v14, v14
	v_fmac_f32_e32 v1, v8, v8
	v_fmac_f32_e32 v6, v11, v11
	v_add_f32_e32 v1, v1, v6
	v_add_f32_e32 v0, v0, v1
	v_add_f32_e32 v0, v10, v0
	ds_bpermute_b32 v1, v120, v0
	global_store_dwordx4 v[12:13], v[2:5], off offset:256 nt
	s_waitcnt lgkmcnt(0)
	v_add_f32_e32 v0, v0, v1
	ds_bpermute_b32 v1, v121, v0
	s_and_saveexec_b64 s[24:25], s[0:1]
	s_cbranch_execz .LBB0_649
	v_lshlrev_b64 v[2:3], 6, v[112:113]
	v_lshl_add_u64 v[2:3], s[62:63], 0, v[2:3]
	v_lshl_add_u64 v[2:3], s[4:5], 2, v[2:3]
	s_lshl_b32 s8, s41, 2
	v_lshl_add_u64 v[2:3], v[2:3], 0, s[8:9]
	s_waitcnt lgkmcnt(0)
	v_add_f32_e32 v0, v0, v1
	global_store_dword v[2:3], v0, off

.LBB0_879:
	v_lshl_or_b32 v178, s14, 8, v195
	v_lshl_add_u32 v182, s50, 8, v193
	v_ashrrev_i32_e32 v179, 31, v178
	v_lshlrev_b64 v[128:129], 1, v[178:179]
	v_ashrrev_i32_e32 v183, 31, v182
	v_lshl_add_u64 v[180:181], s[58:59], 0, v[128:129]
	v_lshlrev_b64 v[130:131], 11, v[182:183]
	v_lshl_add_u64 v[132:133], v[180:181], 0, v[130:131]
	global_load_dwordx4 v[198:201], v[132:133], off
	global_load_dwordx4 v[206:209], v[132:133], off offset:256
	v_or_b32_e32 v188, 16, v182
	v_or_b32_e32 v186, 32, v182
	v_or_b32_e32 v184, 48, v182
	v_ashrrev_i32_e32 v189, 31, v188
	v_ashrrev_i32_e32 v187, 31, v186
	v_ashrrev_i32_e32 v185, 31, v184
	v_lshlrev_b64 v[132:133], 11, v[188:189]
	v_lshlrev_b64 v[134:135], 11, v[186:187]
	v_lshlrev_b64 v[136:137], 11, v[184:185]
	v_lshl_add_u64 v[130:131], s[58:59], 0, v[130:131]
	v_lshl_add_u64 v[132:133], v[180:181], 0, v[132:133]
	v_lshl_add_u64 v[134:135], v[180:181], 0, v[134:135]
	v_lshl_add_u64 v[202:203], v[180:181], 0, v[136:137]
	v_lshl_add_u64 v[210:211], v[130:131], 0, v[128:129]
	global_load_dwordx4 v[148:151], v[132:133], off
	global_load_dwordx4 v[144:147], v[132:133], off offset:256
	global_load_dwordx4 v[140:143], v[134:135], off
	global_load_dwordx4 v[136:139], v[134:135], off offset:256
	s_nop 0
	global_load_dwordx4 v[132:135], v[202:203], off
	global_load_dwordx4 v[128:131], v[202:203], off offset:256
	s_lshl_b32 s26, s14, 2
	s_ashr_i32 s27, s26, 31
	s_waitcnt vmcnt(0)
	v_lshlrev_b32_e32 v202, 16, v198
	v_and_b32_e32 v203, 0xffff0000, v198
	v_lshlrev_b32_e32 v198, 16, v199
	v_and_b32_e32 v199, 0xffff0000, v199
	v_lshlrev_b32_e32 v212, 16, v200
	v_and_b32_e32 v213, 0xffff0000, v200
	v_lshlrev_b32_e32 v200, 16, v201
	v_and_b32_e32 v201, 0xffff0000, v201
	v_lshlrev_b32_e32 v216, 16, v208
	v_and_b32_e32 v217, 0xffff0000, v208
	v_lshlrev_b32_e32 v208, 16, v209
	v_and_b32_e32 v209, 0xffff0000, v209
	v_pk_add_f32 v[126:127], v[126:127], v[198:199]
	v_pk_add_f32 v[124:125], v[124:125], v[202:203]
	v_pk_add_f32 v[122:123], v[122:123], v[200:201]
	v_pk_add_f32 v[120:121], v[120:121], v[212:213]
	v_pk_add_f32 v[198:199], v[114:115], v[208:209]
	v_pk_add_f32 v[200:201], v[112:113], v[216:217]
	v_cvt_pk_bf16_f32 v112, v124, v125
	v_cvt_pk_bf16_f32 v113, v126, v127
	v_cvt_pk_bf16_f32 v114, v120, v121
	v_cvt_pk_bf16_f32 v115, v122, v123
	v_lshlrev_b32_e32 v214, 16, v206
	v_and_b32_e32 v215, 0xffff0000, v206
	v_lshlrev_b32_e32 v206, 16, v207
	v_and_b32_e32 v207, 0xffff0000, v207
	global_store_dwordx4 v[210:211], v[112:115], off nt
	v_lshlrev_b32_e32 v120, 16, v112
	v_lshlrev_b32_e32 v121, 16, v113
	v_and_b32_e32 v112, 0xffff0000, v112
	v_and_b32_e32 v113, 0xffff0000, v113
	v_lshlrev_b32_e32 v122, 16, v114
	v_and_b32_e32 v114, 0xffff0000, v114
	v_lshlrev_b32_e32 v123, 16, v115
	v_and_b32_e32 v115, 0xffff0000, v115
	v_pk_add_f32 v[118:119], v[118:119], v[206:207]
	v_pk_add_f32 v[116:117], v[116:117], v[214:215]
	v_mul_f32_e32 v112, v112, v112
	v_mul_f32_e32 v113, v113, v113
	v_mul_f32_e32 v114, v114, v114
	v_mul_f32_e32 v115, v115, v115
	v_cvt_pk_bf16_f32 v116, v116, v117
	v_cvt_pk_bf16_f32 v117, v118, v119
	v_cvt_pk_bf16_f32 v118, v200, v201
	v_cvt_pk_bf16_f32 v119, v198, v199
	v_fmac_f32_e32 v112, v120, v120
	v_and_b32_e32 v125, 0xffff0000, v116
	v_and_b32_e32 v127, 0xffff0000, v117
	v_and_b32_e32 v198, 0xffff0000, v118
	v_and_b32_e32 v200, 0xffff0000, v119
	v_fmac_f32_e32 v113, v121, v121
	v_fmac_f32_e32 v114, v122, v122
	v_fmac_f32_e32 v115, v123, v123
	v_lshlrev_b32_e32 v124, 16, v116
	v_lshlrev_b32_e32 v126, 16, v117
	v_lshlrev_b32_e32 v197, 16, v118
	v_lshlrev_b32_e32 v199, 16, v119
	v_mul_f32_e32 v120, v125, v125
	v_mul_f32_e32 v121, v127, v127
	v_add_f32_e32 v112, v112, v113
	v_add_f32_e32 v113, v114, v115
	v_mul_f32_e32 v114, v198, v198
	v_mul_f32_e32 v115, v200, v200
	v_fmac_f32_e32 v120, v124, v124
	v_fmac_f32_e32 v121, v126, v126
	v_fmac_f32_e32 v114, v197, v197
	v_fmac_f32_e32 v115, v199, v199
	v_add_f32_e32 v112, v112, v113
	v_add_f32_e32 v113, v120, v121
	v_add_f32_e32 v114, v114, v115
	v_add_f32_e32 v113, v113, v114
	v_and_b32_e32 v114, 64, v191
	v_add_f32_e32 v113, v112, v113
	v_xor_b32_e32 v112, 16, v191
	v_add_u32_e32 v115, 64, v114
	v_cmp_lt_i32_e32 vcc, v112, v115
	global_store_dwordx4 v[210:211], v[116:119], off offset:256 nt
	s_nop 0
	v_cndmask_b32_e32 v112, v191, v112, vcc
	v_lshlrev_b32_e32 v112, 2, v112
	ds_bpermute_b32 v114, v112, v113
	s_waitcnt lgkmcnt(0)
	v_add_f32_e32 v114, v113, v114
	v_xor_b32_e32 v113, 32, v191
	v_cmp_lt_i32_e32 vcc, v113, v115
	s_nop 1
	v_cndmask_b32_e32 v113, v191, v113, vcc
	v_lshlrev_b32_e32 v113, 2, v113
	ds_bpermute_b32 v115, v113, v114
	s_and_saveexec_b64 s[28:29], s[36:37]
	s_cbranch_execz .LBB0_881
	v_lshlrev_b64 v[116:117], 6, v[182:183]
	v_lshl_add_u64 v[116:117], s[62:63], 0, v[116:117]
	v_lshl_add_u64 v[116:117], s[26:27], 2, v[116:117]
	s_lshl_b32 s14, s44, 2
	v_lshl_add_u64 v[116:117], v[116:117], 0, s[14:15]
	s_waitcnt lgkmcnt(0)
	v_add_f32_e32 v114, v114, v115
	global_store_dword v[116:117], v114, off
.LBB0_881:
	s_or_b64 exec, exec, s[28:29]
	v_lshlrev_b32_e32 v116, 16, v148
	v_and_b32_e32 v117, 0xffff0000, v148
	s_waitcnt lgkmcnt(0)
	v_lshlrev_b64 v[114:115], 10, v[188:189]
	v_lshlrev_b32_e32 v120, 16, v150
	v_and_b32_e32 v121, 0xffff0000, v150
	v_lshlrev_b32_e32 v122, 16, v151
	v_and_b32_e32 v123, 0xffff0000, v151
	v_pk_add_f32 v[108:109], v[108:109], v[116:117]
	v_lshlrev_b32_e32 v118, 16, v149
	v_and_b32_e32 v119, 0xffff0000, v149
	v_pk_add_f32 v[116:117], v[106:107], v[122:123]
	v_pk_add_f32 v[106:107], v[104:105], v[120:121]
	v_cvt_pk_bf16_f32 v104, v108, v109
	v_lshl_add_u64 v[108:109], v[114:115], 1, s[58:59]
	v_pk_add_f32 v[110:111], v[110:111], v[118:119]
	v_lshl_add_u64 v[108:109], v[178:179], 1, v[108:109]
	v_cvt_pk_bf16_f32 v105, v110, v111
	v_cvt_pk_bf16_f32 v106, v106, v107
	v_cvt_pk_bf16_f32 v107, v116, v117
	global_store_dwordx4 v[108:109], v[104:107], off nt
	v_lshlrev_b32_e32 v110, 16, v104
	v_lshlrev_b32_e32 v111, 16, v105
	v_and_b32_e32 v104, 0xffff0000, v104
	v_and_b32_e32 v105, 0xffff0000, v105
	v_mul_f32_e32 v104, v104, v104
	v_mul_f32_e32 v105, v105, v105
	v_lshlrev_b32_e32 v114, 16, v106
	v_and_b32_e32 v106, 0xffff0000, v106
	v_lshlrev_b32_e32 v115, 16, v107
	v_and_b32_e32 v107, 0xffff0000, v107
	v_fmac_f32_e32 v104, v110, v110
	v_fmac_f32_e32 v105, v111, v111
	v_add_f32_e32 v104, v104, v105
	v_mul_f32_e32 v105, v106, v106
	v_mul_f32_e32 v106, v107, v107
	v_lshlrev_b32_e32 v124, 16, v144
	v_and_b32_e32 v125, 0xffff0000, v144
	v_lshlrev_b32_e32 v126, 16, v145
	v_and_b32_e32 v127, 0xffff0000, v145
	v_lshlrev_b32_e32 v144, 16, v146
	v_and_b32_e32 v145, 0xffff0000, v146
	v_fmac_f32_e32 v105, v114, v114
	v_fmac_f32_e32 v106, v115, v115
	v_lshlrev_b32_e32 v146, 16, v147
	v_and_b32_e32 v147, 0xffff0000, v147
	v_add_f32_e32 v105, v105, v106
	v_pk_add_f32 v[100:101], v[100:101], v[124:125]
	v_pk_add_f32 v[96:97], v[96:97], v[144:145]
	v_add_f32_e32 v106, v104, v105
	v_pk_add_f32 v[102:103], v[102:103], v[126:127]
	v_pk_add_f32 v[104:105], v[98:99], v[146:147]
	v_cvt_pk_bf16_f32 v98, v100, v101
	v_cvt_pk_bf16_f32 v99, v102, v103
	v_cvt_pk_bf16_f32 v100, v96, v97
	s_nop 0
	v_and_b32_e32 v97, 0xffff0000, v98
	v_lshlrev_b32_e32 v96, 16, v98
	v_and_b32_e32 v103, 0xffff0000, v99
	v_mul_f32_e32 v97, v97, v97
	v_lshlrev_b32_e32 v102, 16, v99
	v_fmac_f32_e32 v97, v96, v96
	v_mul_f32_e32 v96, v103, v103
	v_cvt_pk_bf16_f32 v101, v104, v105
	v_and_b32_e32 v105, 0xffff0000, v100
	v_and_b32_e32 v110, 0xffff0000, v101
	v_fmac_f32_e32 v96, v102, v102
	v_lshlrev_b32_e32 v104, 16, v100
	v_lshlrev_b32_e32 v107, 16, v101
	v_add_f32_e32 v96, v97, v96
	v_mul_f32_e32 v97, v105, v105
	v_mul_f32_e32 v102, v110, v110
	v_fmac_f32_e32 v97, v104, v104
	v_fmac_f32_e32 v102, v107, v107
	v_add_f32_e32 v97, v97, v102
	v_add_f32_e32 v96, v96, v97
	v_add_f32_e32 v96, v106, v96
	ds_bpermute_b32 v97, v112, v96
	global_store_dwordx4 v[108:109], v[98:101], off offset:256 nt
	s_waitcnt lgkmcnt(0)
	v_add_f32_e32 v96, v96, v97
	ds_bpermute_b32 v97, v113, v96
	s_and_saveexec_b64 s[28:29], s[36:37]
	s_cbranch_execz .LBB0_883
	v_lshlrev_b64 v[98:99], 6, v[188:189]
	v_lshl_add_u64 v[98:99], s[62:63], 0, v[98:99]
	v_lshl_add_u64 v[98:99], s[26:27], 2, v[98:99]
	s_lshl_b32 s14, s44, 2
	v_lshl_add_u64 v[98:99], v[98:99], 0, s[14:15]
	s_waitcnt lgkmcnt(0)
	v_add_f32_e32 v96, v96, v97
	global_store_dword v[98:99], v96, off
.LBB0_883:
	s_or_b64 exec, exec, s[28:29]
	v_lshlrev_b32_e32 v98, 16, v140
	v_and_b32_e32 v99, 0xffff0000, v140
	s_waitcnt lgkmcnt(0)
	v_lshlrev_b64 v[96:97], 10, v[186:187]
	v_lshlrev_b32_e32 v102, 16, v142
	v_and_b32_e32 v103, 0xffff0000, v142
	v_lshlrev_b32_e32 v104, 16, v143
	v_and_b32_e32 v105, 0xffff0000, v143
	v_pk_add_f32 v[92:93], v[92:93], v[98:99]
	v_lshlrev_b32_e32 v100, 16, v141
	v_and_b32_e32 v101, 0xffff0000, v141
	v_pk_add_f32 v[98:99], v[90:91], v[104:105]
	v_pk_add_f32 v[90:91], v[88:89], v[102:103]
	v_cvt_pk_bf16_f32 v88, v92, v93
	v_lshl_add_u64 v[92:93], v[96:97], 1, s[58:59]
	v_pk_add_f32 v[94:95], v[94:95], v[100:101]
	v_lshl_add_u64 v[92:93], v[178:179], 1, v[92:93]
	v_cvt_pk_bf16_f32 v89, v94, v95
	v_cvt_pk_bf16_f32 v90, v90, v91
	v_cvt_pk_bf16_f32 v91, v98, v99
	global_store_dwordx4 v[92:93], v[88:91], off nt
	v_lshlrev_b32_e32 v94, 16, v88
	v_lshlrev_b32_e32 v95, 16, v89
	v_and_b32_e32 v88, 0xffff0000, v88
	v_and_b32_e32 v89, 0xffff0000, v89
	v_mul_f32_e32 v88, v88, v88
	v_mul_f32_e32 v89, v89, v89
	v_lshlrev_b32_e32 v96, 16, v90
	v_and_b32_e32 v90, 0xffff0000, v90
	v_lshlrev_b32_e32 v97, 16, v91
	v_and_b32_e32 v91, 0xffff0000, v91
	v_fmac_f32_e32 v88, v94, v94
	v_fmac_f32_e32 v89, v95, v95
	v_add_f32_e32 v88, v88, v89
	v_mul_f32_e32 v89, v90, v90
	v_mul_f32_e32 v90, v91, v91
	v_lshlrev_b32_e32 v106, 16, v136
	v_and_b32_e32 v107, 0xffff0000, v136
	v_lshlrev_b32_e32 v110, 16, v138
	v_and_b32_e32 v111, 0xffff0000, v138
	v_fmac_f32_e32 v89, v96, v96
	v_fmac_f32_e32 v90, v97, v97
	v_lshlrev_b32_e32 v108, 16, v137
	v_and_b32_e32 v109, 0xffff0000, v137
	v_lshlrev_b32_e32 v114, 16, v139
	v_and_b32_e32 v115, 0xffff0000, v139
	v_add_f32_e32 v89, v89, v90
	v_pk_add_f32 v[84:85], v[84:85], v[106:107]
	v_pk_add_f32 v[80:81], v[80:81], v[110:111]
	v_add_f32_e32 v90, v88, v89
	v_pk_add_f32 v[86:87], v[86:87], v[108:109]
	v_pk_add_f32 v[88:89], v[82:83], v[114:115]
	v_cvt_pk_bf16_f32 v82, v84, v85
	v_cvt_pk_bf16_f32 v83, v86, v87
	v_cvt_pk_bf16_f32 v84, v80, v81
	s_nop 0
	v_and_b32_e32 v81, 0xffff0000, v82
	v_lshlrev_b32_e32 v80, 16, v82
	v_and_b32_e32 v87, 0xffff0000, v83
	v_mul_f32_e32 v81, v81, v81
	v_lshlrev_b32_e32 v86, 16, v83
	v_fmac_f32_e32 v81, v80, v80
	v_mul_f32_e32 v80, v87, v87
	v_cvt_pk_bf16_f32 v85, v88, v89
	v_and_b32_e32 v89, 0xffff0000, v84
	v_and_b32_e32 v94, 0xffff0000, v85
	v_fmac_f32_e32 v80, v86, v86
	v_lshlrev_b32_e32 v88, 16, v84
	v_lshlrev_b32_e32 v91, 16, v85
	v_add_f32_e32 v80, v81, v80
	v_mul_f32_e32 v81, v89, v89
	v_mul_f32_e32 v86, v94, v94
	v_fmac_f32_e32 v81, v88, v88
	v_fmac_f32_e32 v86, v91, v91
	v_add_f32_e32 v81, v81, v86
	v_add_f32_e32 v80, v80, v81
	v_add_f32_e32 v80, v90, v80
	ds_bpermute_b32 v81, v112, v80
	global_store_dwordx4 v[92:93], v[82:85], off offset:256 nt
	s_waitcnt lgkmcnt(0)
	v_add_f32_e32 v80, v80, v81
	ds_bpermute_b32 v81, v113, v80
	s_and_saveexec_b64 s[28:29], s[36:37]
	s_cbranch_execz .LBB0_885
	v_lshlrev_b64 v[82:83], 6, v[186:187]
	v_lshl_add_u64 v[82:83], s[62:63], 0, v[82:83]
	v_lshl_add_u64 v[82:83], s[26:27], 2, v[82:83]
	s_lshl_b32 s14, s44, 2
	v_lshl_add_u64 v[82:83], v[82:83], 0, s[14:15]
	s_waitcnt lgkmcnt(0)
	v_add_f32_e32 v80, v80, v81
	global_store_dword v[82:83], v80, off
.LBB0_885:
	s_or_b64 exec, exec, s[28:29]
	v_lshlrev_b32_e32 v82, 16, v132
	v_and_b32_e32 v83, 0xffff0000, v132
	s_waitcnt lgkmcnt(0)
	v_lshlrev_b64 v[80:81], 10, v[184:185]
	v_lshlrev_b32_e32 v86, 16, v134
	v_and_b32_e32 v87, 0xffff0000, v134
	v_lshlrev_b32_e32 v88, 16, v135
	v_and_b32_e32 v89, 0xffff0000, v135
	v_pk_add_f32 v[76:77], v[76:77], v[82:83]
	v_lshlrev_b32_e32 v84, 16, v133
	v_and_b32_e32 v85, 0xffff0000, v133
	v_pk_add_f32 v[82:83], v[74:75], v[88:89]
	v_pk_add_f32 v[74:75], v[72:73], v[86:87]
	v_cvt_pk_bf16_f32 v72, v76, v77
	v_lshl_add_u64 v[76:77], v[80:81], 1, s[58:59]
	v_pk_add_f32 v[78:79], v[78:79], v[84:85]
	v_lshl_add_u64 v[76:77], v[178:179], 1, v[76:77]
	v_cvt_pk_bf16_f32 v73, v78, v79
	v_cvt_pk_bf16_f32 v74, v74, v75
	v_cvt_pk_bf16_f32 v75, v82, v83
	global_store_dwordx4 v[76:77], v[72:75], off nt
	v_lshlrev_b32_e32 v78, 16, v72
	v_lshlrev_b32_e32 v79, 16, v73
	v_and_b32_e32 v72, 0xffff0000, v72
	v_and_b32_e32 v73, 0xffff0000, v73
	v_mul_f32_e32 v72, v72, v72
	v_mul_f32_e32 v73, v73, v73
	v_lshlrev_b32_e32 v80, 16, v74
	v_and_b32_e32 v74, 0xffff0000, v74
	v_lshlrev_b32_e32 v81, 16, v75
	v_and_b32_e32 v75, 0xffff0000, v75
	v_fmac_f32_e32 v72, v78, v78
	v_fmac_f32_e32 v73, v79, v79
	v_add_f32_e32 v72, v72, v73
	v_mul_f32_e32 v73, v74, v74
	v_mul_f32_e32 v74, v75, v75
	v_lshlrev_b32_e32 v90, 16, v128
	v_and_b32_e32 v91, 0xffff0000, v128
	v_lshlrev_b32_e32 v94, 16, v130
	v_and_b32_e32 v95, 0xffff0000, v130
	v_fmac_f32_e32 v73, v80, v80
	v_fmac_f32_e32 v74, v81, v81
	v_lshlrev_b32_e32 v92, 16, v129
	v_and_b32_e32 v93, 0xffff0000, v129
	v_lshlrev_b32_e32 v96, 16, v131
	v_and_b32_e32 v97, 0xffff0000, v131
	v_add_f32_e32 v73, v73, v74
	v_pk_add_f32 v[68:69], v[68:69], v[90:91]
	v_pk_add_f32 v[64:65], v[64:65], v[94:95]
	v_add_f32_e32 v74, v72, v73
	v_pk_add_f32 v[70:71], v[70:71], v[92:93]
	v_pk_add_f32 v[72:73], v[66:67], v[96:97]
	v_cvt_pk_bf16_f32 v66, v68, v69
	v_cvt_pk_bf16_f32 v67, v70, v71
	v_cvt_pk_bf16_f32 v68, v64, v65
	s_nop 0
	v_and_b32_e32 v65, 0xffff0000, v66
	v_lshlrev_b32_e32 v64, 16, v66
	v_and_b32_e32 v71, 0xffff0000, v67
	v_mul_f32_e32 v65, v65, v65
	v_lshlrev_b32_e32 v70, 16, v67
	v_fmac_f32_e32 v65, v64, v64
	v_mul_f32_e32 v64, v71, v71
	v_cvt_pk_bf16_f32 v69, v72, v73
	v_and_b32_e32 v73, 0xffff0000, v68
	v_and_b32_e32 v78, 0xffff0000, v69
	v_fmac_f32_e32 v64, v70, v70
	v_lshlrev_b32_e32 v72, 16, v68
	v_lshlrev_b32_e32 v75, 16, v69
	v_add_f32_e32 v64, v65, v64
	v_mul_f32_e32 v65, v73, v73
	v_mul_f32_e32 v70, v78, v78
	v_fmac_f32_e32 v65, v72, v72
	v_fmac_f32_e32 v70, v75, v75
	v_add_f32_e32 v65, v65, v70
	v_add_f32_e32 v64, v64, v65
	v_add_f32_e32 v64, v74, v64
	ds_bpermute_b32 v65, v112, v64
	global_store_dwordx4 v[76:77], v[66:69], off offset:256 nt
	s_waitcnt lgkmcnt(0)
	v_add_f32_e32 v64, v64, v65
	ds_bpermute_b32 v65, v113, v64
	s_and_saveexec_b64 s[28:29], s[36:37]
	s_cbranch_execz .LBB0_887
	v_lshlrev_b64 v[66:67], 6, v[184:185]
	v_lshl_add_u64 v[66:67], s[62:63], 0, v[66:67]
	v_lshl_add_u64 v[66:67], s[26:27], 2, v[66:67]
	s_lshl_b32 s14, s44, 2
	v_lshl_add_u64 v[66:67], v[66:67], 0, s[14:15]
	s_waitcnt lgkmcnt(0)
	v_add_f32_e32 v64, v64, v65
	global_store_dword v[66:67], v64, off
.LBB0_887:
	s_or_b64 exec, exec, s[28:29]
	v_add_u32_e32 v94, 0x80, v182
	v_ashrrev_i32_e32 v95, 31, v94
	v_lshlrev_b64 v[104:105], 11, v[94:95]
	v_lshl_add_u64 v[68:69], v[180:181], 0, v[104:105]
	s_waitcnt lgkmcnt(0)
	global_load_dwordx4 v[64:67], v[68:69], off
	v_add_u32_e32 v92, 0x90, v182
	v_ashrrev_i32_e32 v93, 31, v92
	v_add_u32_e32 v90, 0xa0, v182
	v_ashrrev_i32_e32 v91, 31, v90
	v_add_u32_e32 v88, 0xb0, v182
	v_ashrrev_i32_e32 v89, 31, v88
	s_waitcnt vmcnt(0)
	v_lshlrev_b32_e32 v106, 16, v64
	v_and_b32_e32 v107, 0xffff0000, v64
	v_lshlrev_b32_e32 v108, 16, v65
	v_and_b32_e32 v109, 0xffff0000, v65
	v_lshlrev_b32_e32 v110, 16, v66
	v_and_b32_e32 v111, 0xffff0000, v66
	v_lshlrev_b32_e32 v114, 16, v67
	v_and_b32_e32 v115, 0xffff0000, v67
	global_load_dwordx4 v[64:67], v[68:69], off offset:256
	v_pk_add_f32 v[60:61], v[60:61], v[106:107]
	v_pk_add_f32 v[56:57], v[56:57], v[110:111]
	v_pk_add_f32 v[62:63], v[62:63], v[108:109]
	v_pk_add_f32 v[106:107], v[58:59], v[114:115]
	s_waitcnt vmcnt(0)
	v_lshlrev_b32_e32 v98, 16, v64
	v_and_b32_e32 v99, 0xffff0000, v64
	v_lshlrev_b32_e32 v102, 16, v65
	v_and_b32_e32 v103, 0xffff0000, v65
	v_lshlrev_b64 v[64:65], 11, v[92:93]
	v_lshl_add_u64 v[64:65], v[180:181], 0, v[64:65]
	global_load_dwordx4 v[84:87], v[64:65], off
	global_load_dwordx4 v[80:83], v[64:65], off offset:256
	v_lshlrev_b64 v[64:65], 11, v[90:91]
	v_lshl_add_u64 v[64:65], v[180:181], 0, v[64:65]
	global_load_dwordx4 v[76:79], v[64:65], off
	global_load_dwordx4 v[72:75], v[64:65], off offset:256
	v_lshlrev_b64 v[64:65], 11, v[88:89]
	v_lshl_add_u64 v[64:65], v[180:181], 0, v[64:65]
	v_lshlrev_b32_e32 v96, 16, v66
	v_and_b32_e32 v97, 0xffff0000, v66
	v_lshlrev_b32_e32 v100, 16, v67
	v_and_b32_e32 v101, 0xffff0000, v67
	global_load_dwordx4 v[68:71], v[64:65], off
	s_nop 0
	global_load_dwordx4 v[64:67], v[64:65], off offset:256
	v_cvt_pk_bf16_f32 v58, v60, v61
	v_cvt_pk_bf16_f32 v59, v62, v63
	v_cvt_pk_bf16_f32 v60, v56, v57
	v_lshl_add_u64 v[56:57], s[58:59], 0, v[104:105]
	v_lshl_add_u64 v[56:57], v[178:179], 1, v[56:57]
	v_cvt_pk_bf16_f32 v61, v106, v107
	global_store_dwordx4 v[56:57], v[58:61], off nt
	v_lshlrev_b32_e32 v62, 16, v58
	v_lshlrev_b32_e32 v63, 16, v59
	v_and_b32_e32 v58, 0xffff0000, v58
	v_and_b32_e32 v59, 0xffff0000, v59
	v_mul_f32_e32 v58, v58, v58
	v_mul_f32_e32 v59, v59, v59
	v_lshlrev_b32_e32 v104, 16, v60
	v_and_b32_e32 v60, 0xffff0000, v60
	v_lshlrev_b32_e32 v105, 16, v61
	v_and_b32_e32 v61, 0xffff0000, v61
	v_fmac_f32_e32 v58, v62, v62
	v_fmac_f32_e32 v59, v63, v63
	v_add_f32_e32 v58, v58, v59
	v_mul_f32_e32 v59, v60, v60
	v_mul_f32_e32 v60, v61, v61
	v_fmac_f32_e32 v59, v104, v104
	v_fmac_f32_e32 v60, v105, v105
	v_add_f32_e32 v59, v59, v60
	v_add_f32_e32 v60, v58, v59
	v_pk_add_f32 v[54:55], v[54:55], v[102:103]
	v_pk_add_f32 v[52:53], v[52:53], v[98:99]
	v_pk_add_f32 v[58:59], v[50:51], v[100:101]
	v_pk_add_f32 v[50:51], v[48:49], v[96:97]
	v_cvt_pk_bf16_f32 v48, v52, v53
	v_cvt_pk_bf16_f32 v49, v54, v55
	s_nop 0
	v_cvt_pk_bf16_f32 v50, v50, v51
	v_cvt_pk_bf16_f32 v51, v58, v59
	global_store_dwordx4 v[56:57], v[48:51], off offset:256 nt
	v_lshlrev_b32_e32 v52, 16, v48
	v_lshlrev_b32_e32 v53, 16, v49
	v_and_b32_e32 v48, 0xffff0000, v48
	v_and_b32_e32 v49, 0xffff0000, v49
	v_mul_f32_e32 v48, v48, v48
	v_mul_f32_e32 v49, v49, v49
	v_lshlrev_b32_e32 v54, 16, v50
	v_and_b32_e32 v50, 0xffff0000, v50
	v_lshlrev_b32_e32 v55, 16, v51
	v_and_b32_e32 v51, 0xffff0000, v51
	v_fmac_f32_e32 v48, v52, v52
	v_fmac_f32_e32 v49, v53, v53
	v_add_f32_e32 v48, v48, v49
	v_mul_f32_e32 v49, v50, v50
	v_mul_f32_e32 v50, v51, v51
	v_fmac_f32_e32 v49, v54, v54
	v_fmac_f32_e32 v50, v55, v55
	v_add_f32_e32 v49, v49, v50
	v_add_f32_e32 v48, v48, v49
	v_add_f32_e32 v48, v60, v48
	ds_bpermute_b32 v49, v112, v48
	s_waitcnt lgkmcnt(0)
	v_add_f32_e32 v48, v48, v49
	ds_bpermute_b32 v49, v113, v48
	s_and_saveexec_b64 s[28:29], s[36:37]
	s_cbranch_execz .LBB0_889
	v_lshlrev_b64 v[50:51], 6, v[94:95]
	v_lshl_add_u64 v[50:51], s[62:63], 0, v[50:51]
	v_lshl_add_u64 v[50:51], s[26:27], 2, v[50:51]
	s_lshl_b32 s14, s44, 2
	v_lshl_add_u64 v[50:51], v[50:51], 0, s[14:15]
	s_waitcnt lgkmcnt(0)
	v_add_f32_e32 v48, v48, v49
	global_store_dword v[50:51], v48, off
.LBB0_889:
	s_or_b64 exec, exec, s[28:29]
	s_waitcnt vmcnt(7)
	v_lshlrev_b32_e32 v50, 16, v84
	v_and_b32_e32 v51, 0xffff0000, v84
	s_waitcnt lgkmcnt(0)
	v_lshlrev_b64 v[48:49], 10, v[92:93]
	v_lshlrev_b32_e32 v54, 16, v86
	v_and_b32_e32 v55, 0xffff0000, v86
	v_lshlrev_b32_e32 v56, 16, v87
	v_and_b32_e32 v57, 0xffff0000, v87
	v_pk_add_f32 v[44:45], v[44:45], v[50:51]
	v_lshlrev_b32_e32 v52, 16, v85
	v_and_b32_e32 v53, 0xffff0000, v85
	v_pk_add_f32 v[50:51], v[42:43], v[56:57]
	v_pk_add_f32 v[42:43], v[40:41], v[54:55]
	v_cvt_pk_bf16_f32 v40, v44, v45
	v_lshl_add_u64 v[44:45], v[48:49], 1, s[58:59]
	v_pk_add_f32 v[46:47], v[46:47], v[52:53]
	v_lshl_add_u64 v[44:45], v[178:179], 1, v[44:45]
	v_cvt_pk_bf16_f32 v41, v46, v47
	v_cvt_pk_bf16_f32 v42, v42, v43
	v_cvt_pk_bf16_f32 v43, v50, v51
	global_store_dwordx4 v[44:45], v[40:43], off nt
	v_lshlrev_b32_e32 v46, 16, v40
	v_lshlrev_b32_e32 v47, 16, v41
	v_and_b32_e32 v40, 0xffff0000, v40
	v_and_b32_e32 v41, 0xffff0000, v41
	v_mul_f32_e32 v40, v40, v40
	v_mul_f32_e32 v41, v41, v41
	v_lshlrev_b32_e32 v48, 16, v42
	v_and_b32_e32 v42, 0xffff0000, v42
	v_lshlrev_b32_e32 v49, 16, v43
	v_and_b32_e32 v43, 0xffff0000, v43
	v_fmac_f32_e32 v40, v46, v46
	v_fmac_f32_e32 v41, v47, v47
	v_add_f32_e32 v40, v40, v41
	v_mul_f32_e32 v41, v42, v42
	v_mul_f32_e32 v42, v43, v43
	s_waitcnt vmcnt(7)
	v_lshlrev_b32_e32 v58, 16, v80
	v_and_b32_e32 v59, 0xffff0000, v80
	v_lshlrev_b32_e32 v62, 16, v82
	v_and_b32_e32 v63, 0xffff0000, v82
	v_fmac_f32_e32 v41, v48, v48
	v_fmac_f32_e32 v42, v49, v49
	v_lshlrev_b32_e32 v60, 16, v81
	v_and_b32_e32 v61, 0xffff0000, v81
	v_lshlrev_b32_e32 v80, 16, v83
	v_and_b32_e32 v81, 0xffff0000, v83
	v_add_f32_e32 v41, v41, v42
	v_pk_add_f32 v[36:37], v[36:37], v[58:59]
	v_pk_add_f32 v[32:33], v[32:33], v[62:63]
	v_add_f32_e32 v42, v40, v41
	v_pk_add_f32 v[38:39], v[38:39], v[60:61]
	v_pk_add_f32 v[40:41], v[34:35], v[80:81]
	v_cvt_pk_bf16_f32 v34, v36, v37
	v_cvt_pk_bf16_f32 v35, v38, v39
	v_cvt_pk_bf16_f32 v36, v32, v33
	s_nop 0
	v_and_b32_e32 v33, 0xffff0000, v34
	v_lshlrev_b32_e32 v32, 16, v34
	v_and_b32_e32 v39, 0xffff0000, v35
	v_mul_f32_e32 v33, v33, v33
	v_lshlrev_b32_e32 v38, 16, v35
	v_fmac_f32_e32 v33, v32, v32
	v_mul_f32_e32 v32, v39, v39
	v_cvt_pk_bf16_f32 v37, v40, v41
	v_and_b32_e32 v41, 0xffff0000, v36
	v_and_b32_e32 v46, 0xffff0000, v37
	v_fmac_f32_e32 v32, v38, v38
	v_lshlrev_b32_e32 v40, 16, v36
	v_lshlrev_b32_e32 v43, 16, v37
	v_add_f32_e32 v32, v33, v32
	v_mul_f32_e32 v33, v41, v41
	v_mul_f32_e32 v38, v46, v46
	v_fmac_f32_e32 v33, v40, v40
	v_fmac_f32_e32 v38, v43, v43
	v_add_f32_e32 v33, v33, v38
	v_add_f32_e32 v32, v32, v33
	v_add_f32_e32 v32, v42, v32
	ds_bpermute_b32 v33, v112, v32
	global_store_dwordx4 v[44:45], v[34:37], off offset:256 nt
	s_waitcnt lgkmcnt(0)
	v_add_f32_e32 v32, v32, v33
	ds_bpermute_b32 v33, v113, v32
	s_and_saveexec_b64 s[28:29], s[36:37]
	s_cbranch_execz .LBB0_891
	v_lshlrev_b64 v[34:35], 6, v[92:93]
	v_lshl_add_u64 v[34:35], s[62:63], 0, v[34:35]
	v_lshl_add_u64 v[34:35], s[26:27], 2, v[34:35]
	s_lshl_b32 s14, s44, 2
	v_lshl_add_u64 v[34:35], v[34:35], 0, s[14:15]
	s_waitcnt lgkmcnt(0)
	v_add_f32_e32 v32, v32, v33
	global_store_dword v[34:35], v32, off
.LBB0_891:
	s_or_b64 exec, exec, s[28:29]
	s_waitcnt vmcnt(7)
	v_lshlrev_b32_e32 v34, 16, v76
	v_and_b32_e32 v35, 0xffff0000, v76
	s_waitcnt lgkmcnt(0)
	v_lshlrev_b64 v[32:33], 10, v[90:91]
	v_lshlrev_b32_e32 v38, 16, v78
	v_and_b32_e32 v39, 0xffff0000, v78
	v_lshlrev_b32_e32 v40, 16, v79
	v_and_b32_e32 v41, 0xffff0000, v79
	v_pk_add_f32 v[28:29], v[28:29], v[34:35]
	v_lshlrev_b32_e32 v36, 16, v77
	v_and_b32_e32 v37, 0xffff0000, v77
	v_pk_add_f32 v[34:35], v[26:27], v[40:41]
	v_pk_add_f32 v[26:27], v[24:25], v[38:39]
	v_cvt_pk_bf16_f32 v24, v28, v29
	v_lshl_add_u64 v[28:29], v[32:33], 1, s[58:59]
	v_pk_add_f32 v[30:31], v[30:31], v[36:37]
	v_lshl_add_u64 v[28:29], v[178:179], 1, v[28:29]
	v_cvt_pk_bf16_f32 v25, v30, v31
	v_cvt_pk_bf16_f32 v26, v26, v27
	v_cvt_pk_bf16_f32 v27, v34, v35
	global_store_dwordx4 v[28:29], v[24:27], off nt
	v_lshlrev_b32_e32 v30, 16, v24
	v_lshlrev_b32_e32 v31, 16, v25
	v_and_b32_e32 v24, 0xffff0000, v24
	v_and_b32_e32 v25, 0xffff0000, v25
	v_mul_f32_e32 v24, v24, v24
	v_mul_f32_e32 v25, v25, v25
	v_lshlrev_b32_e32 v32, 16, v26
	v_and_b32_e32 v26, 0xffff0000, v26
	v_lshlrev_b32_e32 v33, 16, v27
	v_and_b32_e32 v27, 0xffff0000, v27
	v_fmac_f32_e32 v24, v30, v30
	v_fmac_f32_e32 v25, v31, v31
	v_add_f32_e32 v24, v24, v25
	v_mul_f32_e32 v25, v26, v26
	v_mul_f32_e32 v26, v27, v27
	s_waitcnt vmcnt(7)
	v_lshlrev_b32_e32 v42, 16, v72
	v_and_b32_e32 v43, 0xffff0000, v72
	v_lshlrev_b32_e32 v46, 16, v74
	v_and_b32_e32 v47, 0xffff0000, v74
	v_fmac_f32_e32 v25, v32, v32
	v_fmac_f32_e32 v26, v33, v33
	v_lshlrev_b32_e32 v44, 16, v73
	v_and_b32_e32 v45, 0xffff0000, v73
	v_lshlrev_b32_e32 v48, 16, v75
	v_and_b32_e32 v49, 0xffff0000, v75
	v_add_f32_e32 v25, v25, v26
	v_pk_add_f32 v[20:21], v[20:21], v[42:43]
	v_pk_add_f32 v[16:17], v[16:17], v[46:47]
	v_add_f32_e32 v26, v24, v25
	v_pk_add_f32 v[22:23], v[22:23], v[44:45]
	v_pk_add_f32 v[24:25], v[18:19], v[48:49]
	v_cvt_pk_bf16_f32 v18, v20, v21
	v_cvt_pk_bf16_f32 v19, v22, v23
	v_cvt_pk_bf16_f32 v20, v16, v17
	s_nop 0
	v_and_b32_e32 v17, 0xffff0000, v18
	v_lshlrev_b32_e32 v16, 16, v18
	v_and_b32_e32 v23, 0xffff0000, v19
	v_mul_f32_e32 v17, v17, v17
	v_lshlrev_b32_e32 v22, 16, v19
	v_fmac_f32_e32 v17, v16, v16
	v_mul_f32_e32 v16, v23, v23
	v_cvt_pk_bf16_f32 v21, v24, v25
	v_and_b32_e32 v25, 0xffff0000, v20
	v_and_b32_e32 v30, 0xffff0000, v21
	v_fmac_f32_e32 v16, v22, v22
	v_lshlrev_b32_e32 v24, 16, v20
	v_lshlrev_b32_e32 v27, 16, v21
	v_add_f32_e32 v16, v17, v16
	v_mul_f32_e32 v17, v25, v25
	v_mul_f32_e32 v22, v30, v30
	v_fmac_f32_e32 v17, v24, v24
	v_fmac_f32_e32 v22, v27, v27
	v_add_f32_e32 v17, v17, v22
	v_add_f32_e32 v16, v16, v17
	v_add_f32_e32 v16, v26, v16
	ds_bpermute_b32 v17, v112, v16
	global_store_dwordx4 v[28:29], v[18:21], off offset:256 nt
	s_waitcnt lgkmcnt(0)
	v_add_f32_e32 v16, v16, v17
	ds_bpermute_b32 v17, v113, v16
	s_and_saveexec_b64 s[28:29], s[36:37]
	s_cbranch_execz .LBB0_893
	v_lshlrev_b64 v[18:19], 6, v[90:91]
	v_lshl_add_u64 v[18:19], s[62:63], 0, v[18:19]
	v_lshl_add_u64 v[18:19], s[26:27], 2, v[18:19]
	s_lshl_b32 s14, s44, 2
	v_lshl_add_u64 v[18:19], v[18:19], 0, s[14:15]
	s_waitcnt lgkmcnt(0)
	v_add_f32_e32 v16, v16, v17
	global_store_dword v[18:19], v16, off
.LBB0_893:
	s_or_b64 exec, exec, s[28:29]
	s_waitcnt vmcnt(7)
	v_lshlrev_b32_e32 v18, 16, v68
	v_and_b32_e32 v19, 0xffff0000, v68
	s_waitcnt lgkmcnt(0)
	v_lshlrev_b64 v[16:17], 10, v[88:89]
	v_lshlrev_b32_e32 v22, 16, v70
	v_and_b32_e32 v23, 0xffff0000, v70
	v_lshlrev_b32_e32 v24, 16, v71
	v_and_b32_e32 v25, 0xffff0000, v71
	v_pk_add_f32 v[12:13], v[12:13], v[18:19]
	v_lshlrev_b32_e32 v20, 16, v69
	v_and_b32_e32 v21, 0xffff0000, v69
	v_pk_add_f32 v[18:19], v[10:11], v[24:25]
	v_pk_add_f32 v[10:11], v[8:9], v[22:23]
	v_cvt_pk_bf16_f32 v8, v12, v13
	v_lshl_add_u64 v[12:13], v[16:17], 1, s[58:59]
	v_pk_add_f32 v[14:15], v[14:15], v[20:21]
	v_lshl_add_u64 v[12:13], v[178:179], 1, v[12:13]
	v_cvt_pk_bf16_f32 v9, v14, v15
	v_cvt_pk_bf16_f32 v10, v10, v11
	v_cvt_pk_bf16_f32 v11, v18, v19
	global_store_dwordx4 v[12:13], v[8:11], off nt
	v_lshlrev_b32_e32 v14, 16, v8
	v_lshlrev_b32_e32 v15, 16, v9
	v_and_b32_e32 v8, 0xffff0000, v8
	v_and_b32_e32 v9, 0xffff0000, v9
	v_mul_f32_e32 v8, v8, v8
	v_mul_f32_e32 v9, v9, v9
	v_lshlrev_b32_e32 v16, 16, v10
	v_and_b32_e32 v10, 0xffff0000, v10
	v_lshlrev_b32_e32 v17, 16, v11
	v_and_b32_e32 v11, 0xffff0000, v11
	v_fmac_f32_e32 v8, v14, v14
	v_fmac_f32_e32 v9, v15, v15
	v_add_f32_e32 v8, v8, v9
	v_mul_f32_e32 v9, v10, v10
	v_mul_f32_e32 v10, v11, v11
	s_waitcnt vmcnt(7)
	v_lshlrev_b32_e32 v26, 16, v64
	v_and_b32_e32 v27, 0xffff0000, v64
	v_lshlrev_b32_e32 v30, 16, v66
	v_and_b32_e32 v31, 0xffff0000, v66
	v_fmac_f32_e32 v9, v16, v16
	v_fmac_f32_e32 v10, v17, v17
	v_lshlrev_b32_e32 v28, 16, v65
	v_and_b32_e32 v29, 0xffff0000, v65
	v_lshlrev_b32_e32 v32, 16, v67
	v_and_b32_e32 v33, 0xffff0000, v67
	v_add_f32_e32 v9, v9, v10
	v_pk_add_f32 v[4:5], v[4:5], v[26:27]
	v_pk_add_f32 v[0:1], v[0:1], v[30:31]
	v_add_f32_e32 v10, v8, v9
	v_pk_add_f32 v[6:7], v[6:7], v[28:29]
	v_pk_add_f32 v[8:9], v[2:3], v[32:33]
	v_cvt_pk_bf16_f32 v2, v4, v5
	v_cvt_pk_bf16_f32 v3, v6, v7
	v_cvt_pk_bf16_f32 v4, v0, v1
	s_nop 0
	v_and_b32_e32 v1, 0xffff0000, v2
	v_lshlrev_b32_e32 v0, 16, v2
	v_and_b32_e32 v7, 0xffff0000, v3
	v_mul_f32_e32 v1, v1, v1
	v_lshlrev_b32_e32 v6, 16, v3
	v_fmac_f32_e32 v1, v0, v0
	v_mul_f32_e32 v0, v7, v7
	v_cvt_pk_bf16_f32 v5, v8, v9
	v_and_b32_e32 v9, 0xffff0000, v4
	v_and_b32_e32 v14, 0xffff0000, v5
	v_fmac_f32_e32 v0, v6, v6
	v_lshlrev_b32_e32 v8, 16, v4
	v_lshlrev_b32_e32 v11, 16, v5
	v_add_f32_e32 v0, v1, v0
	v_mul_f32_e32 v1, v9, v9
	v_mul_f32_e32 v6, v14, v14
	v_fmac_f32_e32 v1, v8, v8
	v_fmac_f32_e32 v6, v11, v11
	v_add_f32_e32 v1, v1, v6
	v_add_f32_e32 v0, v0, v1
	v_add_f32_e32 v0, v10, v0
	ds_bpermute_b32 v1, v112, v0
	global_store_dwordx4 v[12:13], v[2:5], off offset:256 nt
	s_waitcnt lgkmcnt(0)
	v_add_f32_e32 v0, v0, v1
	ds_bpermute_b32 v1, v113, v0
	s_and_saveexec_b64 s[28:29], s[36:37]
	s_cbranch_execz .LBB0_895
	v_lshlrev_b64 v[2:3], 6, v[88:89]
	v_lshl_add_u64 v[2:3], s[62:63], 0, v[2:3]
	v_lshl_add_u64 v[2:3], s[26:27], 2, v[2:3]
	s_lshl_b32 s14, s44, 2
	v_lshl_add_u64 v[2:3], v[2:3], 0, s[14:15]
	s_waitcnt lgkmcnt(0)
	v_add_f32_e32 v0, v0, v1
	global_store_dword v[2:3], v0, off

.LBB0_1167:
	v_lshl_or_b32 v178, s24, 8, v195
	v_lshl_add_u32 v182, s26, 8, v193
	v_ashrrev_i32_e32 v179, 31, v178
	v_lshlrev_b64 v[128:129], 1, v[178:179]
	v_ashrrev_i32_e32 v183, 31, v182
	v_lshl_add_u64 v[180:181], s[58:59], 0, v[128:129]
	v_lshlrev_b64 v[130:131], 11, v[182:183]
	v_lshl_add_u64 v[132:133], v[180:181], 0, v[130:131]
	global_load_dwordx4 v[198:201], v[132:133], off
	global_load_dwordx4 v[206:209], v[132:133], off offset:256
	v_or_b32_e32 v188, 16, v182
	v_or_b32_e32 v186, 32, v182
	v_or_b32_e32 v184, 48, v182
	v_ashrrev_i32_e32 v189, 31, v188
	v_ashrrev_i32_e32 v187, 31, v186
	v_ashrrev_i32_e32 v185, 31, v184
	v_lshlrev_b64 v[132:133], 11, v[188:189]
	v_lshlrev_b64 v[134:135], 11, v[186:187]
	v_lshlrev_b64 v[136:137], 11, v[184:185]
	v_lshl_add_u64 v[130:131], s[58:59], 0, v[130:131]
	v_lshl_add_u64 v[132:133], v[180:181], 0, v[132:133]
	v_lshl_add_u64 v[134:135], v[180:181], 0, v[134:135]
	v_lshl_add_u64 v[202:203], v[180:181], 0, v[136:137]
	v_lshl_add_u64 v[210:211], v[130:131], 0, v[128:129]
	global_load_dwordx4 v[148:151], v[132:133], off
	global_load_dwordx4 v[144:147], v[132:133], off offset:256
	global_load_dwordx4 v[140:143], v[134:135], off
	global_load_dwordx4 v[136:139], v[134:135], off offset:256
	s_nop 0
	global_load_dwordx4 v[132:135], v[202:203], off
	global_load_dwordx4 v[128:131], v[202:203], off offset:256
	s_lshl_b32 s24, s24, 2
	s_ashr_i32 s25, s24, 31
	s_waitcnt vmcnt(0)
	v_lshlrev_b32_e32 v202, 16, v198
	v_and_b32_e32 v203, 0xffff0000, v198
	v_lshlrev_b32_e32 v198, 16, v199
	v_and_b32_e32 v199, 0xffff0000, v199
	v_lshlrev_b32_e32 v212, 16, v200
	v_and_b32_e32 v213, 0xffff0000, v200
	v_lshlrev_b32_e32 v200, 16, v201
	v_and_b32_e32 v201, 0xffff0000, v201
	v_lshlrev_b32_e32 v216, 16, v208
	v_and_b32_e32 v217, 0xffff0000, v208
	v_lshlrev_b32_e32 v208, 16, v209
	v_and_b32_e32 v209, 0xffff0000, v209
	v_pk_add_f32 v[126:127], v[126:127], v[198:199]
	v_pk_add_f32 v[124:125], v[124:125], v[202:203]
	v_pk_add_f32 v[122:123], v[122:123], v[200:201]
	v_pk_add_f32 v[120:121], v[120:121], v[212:213]
	v_pk_add_f32 v[198:199], v[114:115], v[208:209]
	v_pk_add_f32 v[200:201], v[112:113], v[216:217]
	v_cvt_pk_bf16_f32 v112, v124, v125
	v_cvt_pk_bf16_f32 v113, v126, v127
	v_cvt_pk_bf16_f32 v114, v120, v121
	v_cvt_pk_bf16_f32 v115, v122, v123
	v_lshlrev_b32_e32 v214, 16, v206
	v_and_b32_e32 v215, 0xffff0000, v206
	v_lshlrev_b32_e32 v206, 16, v207
	v_and_b32_e32 v207, 0xffff0000, v207
	global_store_dwordx4 v[210:211], v[112:115], off nt
	v_lshlrev_b32_e32 v120, 16, v112
	v_lshlrev_b32_e32 v121, 16, v113
	v_and_b32_e32 v112, 0xffff0000, v112
	v_and_b32_e32 v113, 0xffff0000, v113
	v_lshlrev_b32_e32 v122, 16, v114
	v_and_b32_e32 v114, 0xffff0000, v114
	v_lshlrev_b32_e32 v123, 16, v115
	v_and_b32_e32 v115, 0xffff0000, v115
	v_pk_add_f32 v[118:119], v[118:119], v[206:207]
	v_pk_add_f32 v[116:117], v[116:117], v[214:215]
	v_mul_f32_e32 v112, v112, v112
	v_mul_f32_e32 v113, v113, v113
	v_mul_f32_e32 v114, v114, v114
	v_mul_f32_e32 v115, v115, v115
	v_cvt_pk_bf16_f32 v116, v116, v117
	v_cvt_pk_bf16_f32 v117, v118, v119
	v_cvt_pk_bf16_f32 v118, v200, v201
	v_cvt_pk_bf16_f32 v119, v198, v199
	v_fmac_f32_e32 v112, v120, v120
	v_and_b32_e32 v125, 0xffff0000, v116
	v_and_b32_e32 v127, 0xffff0000, v117
	v_and_b32_e32 v198, 0xffff0000, v118
	v_and_b32_e32 v200, 0xffff0000, v119
	v_fmac_f32_e32 v113, v121, v121
	v_fmac_f32_e32 v114, v122, v122
	v_fmac_f32_e32 v115, v123, v123
	v_lshlrev_b32_e32 v124, 16, v116
	v_lshlrev_b32_e32 v126, 16, v117
	v_lshlrev_b32_e32 v197, 16, v118
	v_lshlrev_b32_e32 v199, 16, v119
	v_mul_f32_e32 v120, v125, v125
	v_mul_f32_e32 v121, v127, v127
	v_add_f32_e32 v112, v112, v113
	v_add_f32_e32 v113, v114, v115
	v_mul_f32_e32 v114, v198, v198
	v_mul_f32_e32 v115, v200, v200
	v_fmac_f32_e32 v120, v124, v124
	v_fmac_f32_e32 v121, v126, v126
	v_fmac_f32_e32 v114, v197, v197
	v_fmac_f32_e32 v115, v199, v199
	v_add_f32_e32 v112, v112, v113
	v_add_f32_e32 v113, v120, v121
	v_add_f32_e32 v114, v114, v115
	v_add_f32_e32 v113, v113, v114
	v_and_b32_e32 v114, 64, v191
	v_add_f32_e32 v113, v112, v113
	v_xor_b32_e32 v112, 16, v191
	v_add_u32_e32 v115, 64, v114
	v_cmp_lt_i32_e32 vcc, v112, v115
	global_store_dwordx4 v[210:211], v[116:119], off offset:256 nt
	s_nop 0
	v_cndmask_b32_e32 v112, v191, v112, vcc
	v_lshlrev_b32_e32 v112, 2, v112
	ds_bpermute_b32 v114, v112, v113
	s_waitcnt lgkmcnt(0)
	v_add_f32_e32 v114, v113, v114
	v_xor_b32_e32 v113, 32, v191
	v_cmp_lt_i32_e32 vcc, v113, v115
	s_nop 1
	v_cndmask_b32_e32 v113, v191, v113, vcc
	v_lshlrev_b32_e32 v113, 2, v113
	ds_bpermute_b32 v115, v113, v114
	s_and_saveexec_b64 s[26:27], s[36:37]
	s_cbranch_execz .LBB0_1169
	v_lshlrev_b64 v[116:117], 6, v[182:183]
	v_lshl_add_u64 v[116:117], s[62:63], 0, v[116:117]
	v_lshl_add_u64 v[116:117], s[24:25], 2, v[116:117]
	s_lshl_b32 s14, s35, 2
	v_lshl_add_u64 v[116:117], v[116:117], 0, s[14:15]
	s_waitcnt lgkmcnt(0)
	v_add_f32_e32 v114, v114, v115
	global_store_dword v[116:117], v114, off
.LBB0_1169:
	s_or_b64 exec, exec, s[26:27]
	v_lshlrev_b32_e32 v116, 16, v148
	v_and_b32_e32 v117, 0xffff0000, v148
	s_waitcnt lgkmcnt(0)
	v_lshlrev_b64 v[114:115], 10, v[188:189]
	v_lshlrev_b32_e32 v120, 16, v150
	v_and_b32_e32 v121, 0xffff0000, v150
	v_lshlrev_b32_e32 v122, 16, v151
	v_and_b32_e32 v123, 0xffff0000, v151
	v_pk_add_f32 v[108:109], v[108:109], v[116:117]
	v_lshlrev_b32_e32 v118, 16, v149
	v_and_b32_e32 v119, 0xffff0000, v149
	v_pk_add_f32 v[116:117], v[106:107], v[122:123]
	v_pk_add_f32 v[106:107], v[104:105], v[120:121]
	v_cvt_pk_bf16_f32 v104, v108, v109
	v_lshl_add_u64 v[108:109], v[114:115], 1, s[58:59]
	v_pk_add_f32 v[110:111], v[110:111], v[118:119]
	v_lshl_add_u64 v[108:109], v[178:179], 1, v[108:109]
	v_cvt_pk_bf16_f32 v105, v110, v111
	v_cvt_pk_bf16_f32 v106, v106, v107
	v_cvt_pk_bf16_f32 v107, v116, v117
	global_store_dwordx4 v[108:109], v[104:107], off nt
	v_lshlrev_b32_e32 v110, 16, v104
	v_lshlrev_b32_e32 v111, 16, v105
	v_and_b32_e32 v104, 0xffff0000, v104
	v_and_b32_e32 v105, 0xffff0000, v105
	v_mul_f32_e32 v104, v104, v104
	v_mul_f32_e32 v105, v105, v105
	v_lshlrev_b32_e32 v114, 16, v106
	v_and_b32_e32 v106, 0xffff0000, v106
	v_lshlrev_b32_e32 v115, 16, v107
	v_and_b32_e32 v107, 0xffff0000, v107
	v_fmac_f32_e32 v104, v110, v110
	v_fmac_f32_e32 v105, v111, v111
	v_add_f32_e32 v104, v104, v105
	v_mul_f32_e32 v105, v106, v106
	v_mul_f32_e32 v106, v107, v107
	v_lshlrev_b32_e32 v124, 16, v144
	v_and_b32_e32 v125, 0xffff0000, v144
	v_lshlrev_b32_e32 v126, 16, v145
	v_and_b32_e32 v127, 0xffff0000, v145
	v_lshlrev_b32_e32 v144, 16, v146
	v_and_b32_e32 v145, 0xffff0000, v146
	v_fmac_f32_e32 v105, v114, v114
	v_fmac_f32_e32 v106, v115, v115
	v_lshlrev_b32_e32 v146, 16, v147
	v_and_b32_e32 v147, 0xffff0000, v147
	v_add_f32_e32 v105, v105, v106
	v_pk_add_f32 v[100:101], v[100:101], v[124:125]
	v_pk_add_f32 v[96:97], v[96:97], v[144:145]
	v_add_f32_e32 v106, v104, v105
	v_pk_add_f32 v[102:103], v[102:103], v[126:127]
	v_pk_add_f32 v[104:105], v[98:99], v[146:147]
	v_cvt_pk_bf16_f32 v98, v100, v101
	v_cvt_pk_bf16_f32 v99, v102, v103
	v_cvt_pk_bf16_f32 v100, v96, v97
	s_nop 0
	v_and_b32_e32 v97, 0xffff0000, v98
	v_lshlrev_b32_e32 v96, 16, v98
	v_and_b32_e32 v103, 0xffff0000, v99
	v_mul_f32_e32 v97, v97, v97
	v_lshlrev_b32_e32 v102, 16, v99
	v_fmac_f32_e32 v97, v96, v96
	v_mul_f32_e32 v96, v103, v103
	v_cvt_pk_bf16_f32 v101, v104, v105
	v_and_b32_e32 v105, 0xffff0000, v100
	v_and_b32_e32 v110, 0xffff0000, v101
	v_fmac_f32_e32 v96, v102, v102
	v_lshlrev_b32_e32 v104, 16, v100
	v_lshlrev_b32_e32 v107, 16, v101
	v_add_f32_e32 v96, v97, v96
	v_mul_f32_e32 v97, v105, v105
	v_mul_f32_e32 v102, v110, v110
	v_fmac_f32_e32 v97, v104, v104
	v_fmac_f32_e32 v102, v107, v107
	v_add_f32_e32 v97, v97, v102
	v_add_f32_e32 v96, v96, v97
	v_add_f32_e32 v96, v106, v96
	ds_bpermute_b32 v97, v112, v96
	global_store_dwordx4 v[108:109], v[98:101], off offset:256 nt
	s_waitcnt lgkmcnt(0)
	v_add_f32_e32 v96, v96, v97
	ds_bpermute_b32 v97, v113, v96
	s_and_saveexec_b64 s[26:27], s[36:37]
	s_cbranch_execz .LBB0_1171
	v_lshlrev_b64 v[98:99], 6, v[188:189]
	v_lshl_add_u64 v[98:99], s[62:63], 0, v[98:99]
	v_lshl_add_u64 v[98:99], s[24:25], 2, v[98:99]
	s_lshl_b32 s14, s35, 2
	v_lshl_add_u64 v[98:99], v[98:99], 0, s[14:15]
	s_waitcnt lgkmcnt(0)
	v_add_f32_e32 v96, v96, v97
	global_store_dword v[98:99], v96, off
.LBB0_1171:
	s_or_b64 exec, exec, s[26:27]
	v_lshlrev_b32_e32 v98, 16, v140
	v_and_b32_e32 v99, 0xffff0000, v140
	s_waitcnt lgkmcnt(0)
	v_lshlrev_b64 v[96:97], 10, v[186:187]
	v_lshlrev_b32_e32 v102, 16, v142
	v_and_b32_e32 v103, 0xffff0000, v142
	v_lshlrev_b32_e32 v104, 16, v143
	v_and_b32_e32 v105, 0xffff0000, v143
	v_pk_add_f32 v[92:93], v[92:93], v[98:99]
	v_lshlrev_b32_e32 v100, 16, v141
	v_and_b32_e32 v101, 0xffff0000, v141
	v_pk_add_f32 v[98:99], v[90:91], v[104:105]
	v_pk_add_f32 v[90:91], v[88:89], v[102:103]
	v_cvt_pk_bf16_f32 v88, v92, v93
	v_lshl_add_u64 v[92:93], v[96:97], 1, s[58:59]
	v_pk_add_f32 v[94:95], v[94:95], v[100:101]
	v_lshl_add_u64 v[92:93], v[178:179], 1, v[92:93]
	v_cvt_pk_bf16_f32 v89, v94, v95
	v_cvt_pk_bf16_f32 v90, v90, v91
	v_cvt_pk_bf16_f32 v91, v98, v99
	global_store_dwordx4 v[92:93], v[88:91], off nt
	v_lshlrev_b32_e32 v94, 16, v88
	v_lshlrev_b32_e32 v95, 16, v89
	v_and_b32_e32 v88, 0xffff0000, v88
	v_and_b32_e32 v89, 0xffff0000, v89
	v_mul_f32_e32 v88, v88, v88
	v_mul_f32_e32 v89, v89, v89
	v_lshlrev_b32_e32 v96, 16, v90
	v_and_b32_e32 v90, 0xffff0000, v90
	v_lshlrev_b32_e32 v97, 16, v91
	v_and_b32_e32 v91, 0xffff0000, v91
	v_fmac_f32_e32 v88, v94, v94
	v_fmac_f32_e32 v89, v95, v95
	v_add_f32_e32 v88, v88, v89
	v_mul_f32_e32 v89, v90, v90
	v_mul_f32_e32 v90, v91, v91
	v_lshlrev_b32_e32 v106, 16, v136
	v_and_b32_e32 v107, 0xffff0000, v136
	v_lshlrev_b32_e32 v110, 16, v138
	v_and_b32_e32 v111, 0xffff0000, v138
	v_fmac_f32_e32 v89, v96, v96
	v_fmac_f32_e32 v90, v97, v97
	v_lshlrev_b32_e32 v108, 16, v137
	v_and_b32_e32 v109, 0xffff0000, v137
	v_lshlrev_b32_e32 v114, 16, v139
	v_and_b32_e32 v115, 0xffff0000, v139
	v_add_f32_e32 v89, v89, v90
	v_pk_add_f32 v[84:85], v[84:85], v[106:107]
	v_pk_add_f32 v[80:81], v[80:81], v[110:111]
	v_add_f32_e32 v90, v88, v89
	v_pk_add_f32 v[86:87], v[86:87], v[108:109]
	v_pk_add_f32 v[88:89], v[82:83], v[114:115]
	v_cvt_pk_bf16_f32 v82, v84, v85
	v_cvt_pk_bf16_f32 v83, v86, v87
	v_cvt_pk_bf16_f32 v84, v80, v81
	s_nop 0
	v_and_b32_e32 v81, 0xffff0000, v82
	v_lshlrev_b32_e32 v80, 16, v82
	v_and_b32_e32 v87, 0xffff0000, v83
	v_mul_f32_e32 v81, v81, v81
	v_lshlrev_b32_e32 v86, 16, v83
	v_fmac_f32_e32 v81, v80, v80
	v_mul_f32_e32 v80, v87, v87
	v_cvt_pk_bf16_f32 v85, v88, v89
	v_and_b32_e32 v89, 0xffff0000, v84
	v_and_b32_e32 v94, 0xffff0000, v85
	v_fmac_f32_e32 v80, v86, v86
	v_lshlrev_b32_e32 v88, 16, v84
	v_lshlrev_b32_e32 v91, 16, v85
	v_add_f32_e32 v80, v81, v80
	v_mul_f32_e32 v81, v89, v89
	v_mul_f32_e32 v86, v94, v94
	v_fmac_f32_e32 v81, v88, v88
	v_fmac_f32_e32 v86, v91, v91
	v_add_f32_e32 v81, v81, v86
	v_add_f32_e32 v80, v80, v81
	v_add_f32_e32 v80, v90, v80
	ds_bpermute_b32 v81, v112, v80
	global_store_dwordx4 v[92:93], v[82:85], off offset:256 nt
	s_waitcnt lgkmcnt(0)
	v_add_f32_e32 v80, v80, v81
	ds_bpermute_b32 v81, v113, v80
	s_and_saveexec_b64 s[26:27], s[36:37]
	s_cbranch_execz .LBB0_1173
	v_lshlrev_b64 v[82:83], 6, v[186:187]
	v_lshl_add_u64 v[82:83], s[62:63], 0, v[82:83]
	v_lshl_add_u64 v[82:83], s[24:25], 2, v[82:83]
	s_lshl_b32 s14, s35, 2
	v_lshl_add_u64 v[82:83], v[82:83], 0, s[14:15]
	s_waitcnt lgkmcnt(0)
	v_add_f32_e32 v80, v80, v81
	global_store_dword v[82:83], v80, off
.LBB0_1173:
	s_or_b64 exec, exec, s[26:27]
	v_lshlrev_b32_e32 v82, 16, v132
	v_and_b32_e32 v83, 0xffff0000, v132
	s_waitcnt lgkmcnt(0)
	v_lshlrev_b64 v[80:81], 10, v[184:185]
	v_lshlrev_b32_e32 v86, 16, v134
	v_and_b32_e32 v87, 0xffff0000, v134
	v_lshlrev_b32_e32 v88, 16, v135
	v_and_b32_e32 v89, 0xffff0000, v135
	v_pk_add_f32 v[76:77], v[76:77], v[82:83]
	v_lshlrev_b32_e32 v84, 16, v133
	v_and_b32_e32 v85, 0xffff0000, v133
	v_pk_add_f32 v[82:83], v[74:75], v[88:89]
	v_pk_add_f32 v[74:75], v[72:73], v[86:87]
	v_cvt_pk_bf16_f32 v72, v76, v77
	v_lshl_add_u64 v[76:77], v[80:81], 1, s[58:59]
	v_pk_add_f32 v[78:79], v[78:79], v[84:85]
	v_lshl_add_u64 v[76:77], v[178:179], 1, v[76:77]
	v_cvt_pk_bf16_f32 v73, v78, v79
	v_cvt_pk_bf16_f32 v74, v74, v75
	v_cvt_pk_bf16_f32 v75, v82, v83
	global_store_dwordx4 v[76:77], v[72:75], off nt
	v_lshlrev_b32_e32 v78, 16, v72
	v_lshlrev_b32_e32 v79, 16, v73
	v_and_b32_e32 v72, 0xffff0000, v72
	v_and_b32_e32 v73, 0xffff0000, v73
	v_mul_f32_e32 v72, v72, v72
	v_mul_f32_e32 v73, v73, v73
	v_lshlrev_b32_e32 v80, 16, v74
	v_and_b32_e32 v74, 0xffff0000, v74
	v_lshlrev_b32_e32 v81, 16, v75
	v_and_b32_e32 v75, 0xffff0000, v75
	v_fmac_f32_e32 v72, v78, v78
	v_fmac_f32_e32 v73, v79, v79
	v_add_f32_e32 v72, v72, v73
	v_mul_f32_e32 v73, v74, v74
	v_mul_f32_e32 v74, v75, v75
	v_lshlrev_b32_e32 v90, 16, v128
	v_and_b32_e32 v91, 0xffff0000, v128
	v_lshlrev_b32_e32 v94, 16, v130
	v_and_b32_e32 v95, 0xffff0000, v130
	v_fmac_f32_e32 v73, v80, v80
	v_fmac_f32_e32 v74, v81, v81
	v_lshlrev_b32_e32 v92, 16, v129
	v_and_b32_e32 v93, 0xffff0000, v129
	v_lshlrev_b32_e32 v96, 16, v131
	v_and_b32_e32 v97, 0xffff0000, v131
	v_add_f32_e32 v73, v73, v74
	v_pk_add_f32 v[68:69], v[68:69], v[90:91]
	v_pk_add_f32 v[64:65], v[64:65], v[94:95]
	v_add_f32_e32 v74, v72, v73
	v_pk_add_f32 v[70:71], v[70:71], v[92:93]
	v_pk_add_f32 v[72:73], v[66:67], v[96:97]
	v_cvt_pk_bf16_f32 v66, v68, v69
	v_cvt_pk_bf16_f32 v67, v70, v71
	v_cvt_pk_bf16_f32 v68, v64, v65
	s_nop 0
	v_and_b32_e32 v65, 0xffff0000, v66
	v_lshlrev_b32_e32 v64, 16, v66
	v_and_b32_e32 v71, 0xffff0000, v67
	v_mul_f32_e32 v65, v65, v65
	v_lshlrev_b32_e32 v70, 16, v67
	v_fmac_f32_e32 v65, v64, v64
	v_mul_f32_e32 v64, v71, v71
	v_cvt_pk_bf16_f32 v69, v72, v73
	v_and_b32_e32 v73, 0xffff0000, v68
	v_and_b32_e32 v78, 0xffff0000, v69
	v_fmac_f32_e32 v64, v70, v70
	v_lshlrev_b32_e32 v72, 16, v68
	v_lshlrev_b32_e32 v75, 16, v69
	v_add_f32_e32 v64, v65, v64
	v_mul_f32_e32 v65, v73, v73
	v_mul_f32_e32 v70, v78, v78
	v_fmac_f32_e32 v65, v72, v72
	v_fmac_f32_e32 v70, v75, v75
	v_add_f32_e32 v65, v65, v70
	v_add_f32_e32 v64, v64, v65
	v_add_f32_e32 v64, v74, v64
	ds_bpermute_b32 v65, v112, v64
	global_store_dwordx4 v[76:77], v[66:69], off offset:256 nt
	s_waitcnt lgkmcnt(0)
	v_add_f32_e32 v64, v64, v65
	ds_bpermute_b32 v65, v113, v64
	s_and_saveexec_b64 s[26:27], s[36:37]
	s_cbranch_execz .LBB0_1175
	v_lshlrev_b64 v[66:67], 6, v[184:185]
	v_lshl_add_u64 v[66:67], s[62:63], 0, v[66:67]
	v_lshl_add_u64 v[66:67], s[24:25], 2, v[66:67]
	s_lshl_b32 s14, s35, 2
	v_lshl_add_u64 v[66:67], v[66:67], 0, s[14:15]
	s_waitcnt lgkmcnt(0)
	v_add_f32_e32 v64, v64, v65
	global_store_dword v[66:67], v64, off
.LBB0_1175:
	s_or_b64 exec, exec, s[26:27]
	v_add_u32_e32 v94, 0x80, v182
	v_ashrrev_i32_e32 v95, 31, v94
	v_lshlrev_b64 v[104:105], 11, v[94:95]
	v_lshl_add_u64 v[68:69], v[180:181], 0, v[104:105]
	s_waitcnt lgkmcnt(0)
	global_load_dwordx4 v[64:67], v[68:69], off
	v_add_u32_e32 v92, 0x90, v182
	v_ashrrev_i32_e32 v93, 31, v92
	v_add_u32_e32 v90, 0xa0, v182
	v_ashrrev_i32_e32 v91, 31, v90
	v_add_u32_e32 v88, 0xb0, v182
	v_ashrrev_i32_e32 v89, 31, v88
	s_waitcnt vmcnt(0)
	v_lshlrev_b32_e32 v106, 16, v64
	v_and_b32_e32 v107, 0xffff0000, v64
	v_lshlrev_b32_e32 v108, 16, v65
	v_and_b32_e32 v109, 0xffff0000, v65
	v_lshlrev_b32_e32 v110, 16, v66
	v_and_b32_e32 v111, 0xffff0000, v66
	v_lshlrev_b32_e32 v114, 16, v67
	v_and_b32_e32 v115, 0xffff0000, v67
	global_load_dwordx4 v[64:67], v[68:69], off offset:256
	v_pk_add_f32 v[60:61], v[60:61], v[106:107]
	v_pk_add_f32 v[56:57], v[56:57], v[110:111]
	v_pk_add_f32 v[62:63], v[62:63], v[108:109]
	v_pk_add_f32 v[106:107], v[58:59], v[114:115]
	s_waitcnt vmcnt(0)
	v_lshlrev_b32_e32 v98, 16, v64
	v_and_b32_e32 v99, 0xffff0000, v64
	v_lshlrev_b32_e32 v102, 16, v65
	v_and_b32_e32 v103, 0xffff0000, v65
	v_lshlrev_b64 v[64:65], 11, v[92:93]
	v_lshl_add_u64 v[64:65], v[180:181], 0, v[64:65]
	global_load_dwordx4 v[84:87], v[64:65], off
	global_load_dwordx4 v[80:83], v[64:65], off offset:256
	v_lshlrev_b64 v[64:65], 11, v[90:91]
	v_lshl_add_u64 v[64:65], v[180:181], 0, v[64:65]
	global_load_dwordx4 v[76:79], v[64:65], off
	global_load_dwordx4 v[72:75], v[64:65], off offset:256
	v_lshlrev_b64 v[64:65], 11, v[88:89]
	v_lshl_add_u64 v[64:65], v[180:181], 0, v[64:65]
	v_lshlrev_b32_e32 v96, 16, v66
	v_and_b32_e32 v97, 0xffff0000, v66
	v_lshlrev_b32_e32 v100, 16, v67
	v_and_b32_e32 v101, 0xffff0000, v67
	global_load_dwordx4 v[68:71], v[64:65], off
	s_nop 0
	global_load_dwordx4 v[64:67], v[64:65], off offset:256
	v_cvt_pk_bf16_f32 v58, v60, v61
	v_cvt_pk_bf16_f32 v59, v62, v63
	v_cvt_pk_bf16_f32 v60, v56, v57
	v_lshl_add_u64 v[56:57], s[58:59], 0, v[104:105]
	v_lshl_add_u64 v[56:57], v[178:179], 1, v[56:57]
	v_cvt_pk_bf16_f32 v61, v106, v107
	global_store_dwordx4 v[56:57], v[58:61], off nt
	v_lshlrev_b32_e32 v62, 16, v58
	v_lshlrev_b32_e32 v63, 16, v59
	v_and_b32_e32 v58, 0xffff0000, v58
	v_and_b32_e32 v59, 0xffff0000, v59
	v_mul_f32_e32 v58, v58, v58
	v_mul_f32_e32 v59, v59, v59
	v_lshlrev_b32_e32 v104, 16, v60
	v_and_b32_e32 v60, 0xffff0000, v60
	v_lshlrev_b32_e32 v105, 16, v61
	v_and_b32_e32 v61, 0xffff0000, v61
	v_fmac_f32_e32 v58, v62, v62
	v_fmac_f32_e32 v59, v63, v63
	v_add_f32_e32 v58, v58, v59
	v_mul_f32_e32 v59, v60, v60
	v_mul_f32_e32 v60, v61, v61
	v_fmac_f32_e32 v59, v104, v104
	v_fmac_f32_e32 v60, v105, v105
	v_add_f32_e32 v59, v59, v60
	v_add_f32_e32 v60, v58, v59
	v_pk_add_f32 v[54:55], v[54:55], v[102:103]
	v_pk_add_f32 v[52:53], v[52:53], v[98:99]
	v_pk_add_f32 v[58:59], v[50:51], v[100:101]
	v_pk_add_f32 v[50:51], v[48:49], v[96:97]
	v_cvt_pk_bf16_f32 v48, v52, v53
	v_cvt_pk_bf16_f32 v49, v54, v55
	s_nop 0
	v_cvt_pk_bf16_f32 v50, v50, v51
	v_cvt_pk_bf16_f32 v51, v58, v59
	global_store_dwordx4 v[56:57], v[48:51], off offset:256 nt
	v_lshlrev_b32_e32 v52, 16, v48
	v_lshlrev_b32_e32 v53, 16, v49
	v_and_b32_e32 v48, 0xffff0000, v48
	v_and_b32_e32 v49, 0xffff0000, v49
	v_mul_f32_e32 v48, v48, v48
	v_mul_f32_e32 v49, v49, v49
	v_lshlrev_b32_e32 v54, 16, v50
	v_and_b32_e32 v50, 0xffff0000, v50
	v_lshlrev_b32_e32 v55, 16, v51
	v_and_b32_e32 v51, 0xffff0000, v51
	v_fmac_f32_e32 v48, v52, v52
	v_fmac_f32_e32 v49, v53, v53
	v_add_f32_e32 v48, v48, v49
	v_mul_f32_e32 v49, v50, v50
	v_mul_f32_e32 v50, v51, v51
	v_fmac_f32_e32 v49, v54, v54
	v_fmac_f32_e32 v50, v55, v55
	v_add_f32_e32 v49, v49, v50
	v_add_f32_e32 v48, v48, v49
	v_add_f32_e32 v48, v60, v48
	ds_bpermute_b32 v49, v112, v48
	s_waitcnt lgkmcnt(0)
	v_add_f32_e32 v48, v48, v49
	ds_bpermute_b32 v49, v113, v48
	s_and_saveexec_b64 s[26:27], s[36:37]
	s_cbranch_execz .LBB0_1177
	v_lshlrev_b64 v[50:51], 6, v[94:95]
	v_lshl_add_u64 v[50:51], s[62:63], 0, v[50:51]
	v_lshl_add_u64 v[50:51], s[24:25], 2, v[50:51]
	s_lshl_b32 s14, s35, 2
	v_lshl_add_u64 v[50:51], v[50:51], 0, s[14:15]
	s_waitcnt lgkmcnt(0)
	v_add_f32_e32 v48, v48, v49
	global_store_dword v[50:51], v48, off
.LBB0_1177:
	s_or_b64 exec, exec, s[26:27]
	s_waitcnt vmcnt(7)
	v_lshlrev_b32_e32 v50, 16, v84
	v_and_b32_e32 v51, 0xffff0000, v84
	s_waitcnt lgkmcnt(0)
	v_lshlrev_b64 v[48:49], 10, v[92:93]
	v_lshlrev_b32_e32 v54, 16, v86
	v_and_b32_e32 v55, 0xffff0000, v86
	v_lshlrev_b32_e32 v56, 16, v87
	v_and_b32_e32 v57, 0xffff0000, v87
	v_pk_add_f32 v[44:45], v[44:45], v[50:51]
	v_lshlrev_b32_e32 v52, 16, v85
	v_and_b32_e32 v53, 0xffff0000, v85
	v_pk_add_f32 v[50:51], v[42:43], v[56:57]
	v_pk_add_f32 v[42:43], v[40:41], v[54:55]
	v_cvt_pk_bf16_f32 v40, v44, v45
	v_lshl_add_u64 v[44:45], v[48:49], 1, s[58:59]
	v_pk_add_f32 v[46:47], v[46:47], v[52:53]
	v_lshl_add_u64 v[44:45], v[178:179], 1, v[44:45]
	v_cvt_pk_bf16_f32 v41, v46, v47
	v_cvt_pk_bf16_f32 v42, v42, v43
	v_cvt_pk_bf16_f32 v43, v50, v51
	global_store_dwordx4 v[44:45], v[40:43], off nt
	v_lshlrev_b32_e32 v46, 16, v40
	v_lshlrev_b32_e32 v47, 16, v41
	v_and_b32_e32 v40, 0xffff0000, v40
	v_and_b32_e32 v41, 0xffff0000, v41
	v_mul_f32_e32 v40, v40, v40
	v_mul_f32_e32 v41, v41, v41
	v_lshlrev_b32_e32 v48, 16, v42
	v_and_b32_e32 v42, 0xffff0000, v42
	v_lshlrev_b32_e32 v49, 16, v43
	v_and_b32_e32 v43, 0xffff0000, v43
	v_fmac_f32_e32 v40, v46, v46
	v_fmac_f32_e32 v41, v47, v47
	v_add_f32_e32 v40, v40, v41
	v_mul_f32_e32 v41, v42, v42
	v_mul_f32_e32 v42, v43, v43
	s_waitcnt vmcnt(7)
	v_lshlrev_b32_e32 v58, 16, v80
	v_and_b32_e32 v59, 0xffff0000, v80
	v_lshlrev_b32_e32 v62, 16, v82
	v_and_b32_e32 v63, 0xffff0000, v82
	v_fmac_f32_e32 v41, v48, v48
	v_fmac_f32_e32 v42, v49, v49
	v_lshlrev_b32_e32 v60, 16, v81
	v_and_b32_e32 v61, 0xffff0000, v81
	v_lshlrev_b32_e32 v80, 16, v83
	v_and_b32_e32 v81, 0xffff0000, v83
	v_add_f32_e32 v41, v41, v42
	v_pk_add_f32 v[36:37], v[36:37], v[58:59]
	v_pk_add_f32 v[32:33], v[32:33], v[62:63]
	v_add_f32_e32 v42, v40, v41
	v_pk_add_f32 v[38:39], v[38:39], v[60:61]
	v_pk_add_f32 v[40:41], v[34:35], v[80:81]
	v_cvt_pk_bf16_f32 v34, v36, v37
	v_cvt_pk_bf16_f32 v35, v38, v39
	v_cvt_pk_bf16_f32 v36, v32, v33
	s_nop 0
	v_and_b32_e32 v33, 0xffff0000, v34
	v_lshlrev_b32_e32 v32, 16, v34
	v_and_b32_e32 v39, 0xffff0000, v35
	v_mul_f32_e32 v33, v33, v33
	v_lshlrev_b32_e32 v38, 16, v35
	v_fmac_f32_e32 v33, v32, v32
	v_mul_f32_e32 v32, v39, v39
	v_cvt_pk_bf16_f32 v37, v40, v41
	v_and_b32_e32 v41, 0xffff0000, v36
	v_and_b32_e32 v46, 0xffff0000, v37
	v_fmac_f32_e32 v32, v38, v38
	v_lshlrev_b32_e32 v40, 16, v36
	v_lshlrev_b32_e32 v43, 16, v37
	v_add_f32_e32 v32, v33, v32
	v_mul_f32_e32 v33, v41, v41
	v_mul_f32_e32 v38, v46, v46
	v_fmac_f32_e32 v33, v40, v40
	v_fmac_f32_e32 v38, v43, v43
	v_add_f32_e32 v33, v33, v38
	v_add_f32_e32 v32, v32, v33
	v_add_f32_e32 v32, v42, v32
	ds_bpermute_b32 v33, v112, v32
	global_store_dwordx4 v[44:45], v[34:37], off offset:256 nt
	s_waitcnt lgkmcnt(0)
	v_add_f32_e32 v32, v32, v33
	ds_bpermute_b32 v33, v113, v32
	s_and_saveexec_b64 s[26:27], s[36:37]
	s_cbranch_execz .LBB0_1179
	v_lshlrev_b64 v[34:35], 6, v[92:93]
	v_lshl_add_u64 v[34:35], s[62:63], 0, v[34:35]
	v_lshl_add_u64 v[34:35], s[24:25], 2, v[34:35]
	s_lshl_b32 s14, s35, 2
	v_lshl_add_u64 v[34:35], v[34:35], 0, s[14:15]
	s_waitcnt lgkmcnt(0)
	v_add_f32_e32 v32, v32, v33
	global_store_dword v[34:35], v32, off
.LBB0_1179:
	s_or_b64 exec, exec, s[26:27]
	s_waitcnt vmcnt(7)
	v_lshlrev_b32_e32 v34, 16, v76
	v_and_b32_e32 v35, 0xffff0000, v76
	s_waitcnt lgkmcnt(0)
	v_lshlrev_b64 v[32:33], 10, v[90:91]
	v_lshlrev_b32_e32 v38, 16, v78
	v_and_b32_e32 v39, 0xffff0000, v78
	v_lshlrev_b32_e32 v40, 16, v79
	v_and_b32_e32 v41, 0xffff0000, v79
	v_pk_add_f32 v[28:29], v[28:29], v[34:35]
	v_lshlrev_b32_e32 v36, 16, v77
	v_and_b32_e32 v37, 0xffff0000, v77
	v_pk_add_f32 v[34:35], v[26:27], v[40:41]
	v_pk_add_f32 v[26:27], v[24:25], v[38:39]
	v_cvt_pk_bf16_f32 v24, v28, v29
	v_lshl_add_u64 v[28:29], v[32:33], 1, s[58:59]
	v_pk_add_f32 v[30:31], v[30:31], v[36:37]
	v_lshl_add_u64 v[28:29], v[178:179], 1, v[28:29]
	v_cvt_pk_bf16_f32 v25, v30, v31
	v_cvt_pk_bf16_f32 v26, v26, v27
	v_cvt_pk_bf16_f32 v27, v34, v35
	global_store_dwordx4 v[28:29], v[24:27], off nt
	v_lshlrev_b32_e32 v30, 16, v24
	v_lshlrev_b32_e32 v31, 16, v25
	v_and_b32_e32 v24, 0xffff0000, v24
	v_and_b32_e32 v25, 0xffff0000, v25
	v_mul_f32_e32 v24, v24, v24
	v_mul_f32_e32 v25, v25, v25
	v_lshlrev_b32_e32 v32, 16, v26
	v_and_b32_e32 v26, 0xffff0000, v26
	v_lshlrev_b32_e32 v33, 16, v27
	v_and_b32_e32 v27, 0xffff0000, v27
	v_fmac_f32_e32 v24, v30, v30
	v_fmac_f32_e32 v25, v31, v31
	v_add_f32_e32 v24, v24, v25
	v_mul_f32_e32 v25, v26, v26
	v_mul_f32_e32 v26, v27, v27
	s_waitcnt vmcnt(7)
	v_lshlrev_b32_e32 v42, 16, v72
	v_and_b32_e32 v43, 0xffff0000, v72
	v_lshlrev_b32_e32 v46, 16, v74
	v_and_b32_e32 v47, 0xffff0000, v74
	v_fmac_f32_e32 v25, v32, v32
	v_fmac_f32_e32 v26, v33, v33
	v_lshlrev_b32_e32 v44, 16, v73
	v_and_b32_e32 v45, 0xffff0000, v73
	v_lshlrev_b32_e32 v48, 16, v75
	v_and_b32_e32 v49, 0xffff0000, v75
	v_add_f32_e32 v25, v25, v26
	v_pk_add_f32 v[20:21], v[20:21], v[42:43]
	v_pk_add_f32 v[16:17], v[16:17], v[46:47]
	v_add_f32_e32 v26, v24, v25
	v_pk_add_f32 v[22:23], v[22:23], v[44:45]
	v_pk_add_f32 v[24:25], v[18:19], v[48:49]
	v_cvt_pk_bf16_f32 v18, v20, v21
	v_cvt_pk_bf16_f32 v19, v22, v23
	v_cvt_pk_bf16_f32 v20, v16, v17
	s_nop 0
	v_and_b32_e32 v17, 0xffff0000, v18
	v_lshlrev_b32_e32 v16, 16, v18
	v_and_b32_e32 v23, 0xffff0000, v19
	v_mul_f32_e32 v17, v17, v17
	v_lshlrev_b32_e32 v22, 16, v19
	v_fmac_f32_e32 v17, v16, v16
	v_mul_f32_e32 v16, v23, v23
	v_cvt_pk_bf16_f32 v21, v24, v25
	v_and_b32_e32 v25, 0xffff0000, v20
	v_and_b32_e32 v30, 0xffff0000, v21
	v_fmac_f32_e32 v16, v22, v22
	v_lshlrev_b32_e32 v24, 16, v20
	v_lshlrev_b32_e32 v27, 16, v21
	v_add_f32_e32 v16, v17, v16
	v_mul_f32_e32 v17, v25, v25
	v_mul_f32_e32 v22, v30, v30
	v_fmac_f32_e32 v17, v24, v24
	v_fmac_f32_e32 v22, v27, v27
	v_add_f32_e32 v17, v17, v22
	v_add_f32_e32 v16, v16, v17
	v_add_f32_e32 v16, v26, v16
	ds_bpermute_b32 v17, v112, v16
	global_store_dwordx4 v[28:29], v[18:21], off offset:256 nt
	s_waitcnt lgkmcnt(0)
	v_add_f32_e32 v16, v16, v17
	ds_bpermute_b32 v17, v113, v16
	s_and_saveexec_b64 s[26:27], s[36:37]
	s_cbranch_execz .LBB0_1181
	v_lshlrev_b64 v[18:19], 6, v[90:91]
	v_lshl_add_u64 v[18:19], s[62:63], 0, v[18:19]
	v_lshl_add_u64 v[18:19], s[24:25], 2, v[18:19]
	s_lshl_b32 s14, s35, 2
	v_lshl_add_u64 v[18:19], v[18:19], 0, s[14:15]
	s_waitcnt lgkmcnt(0)
	v_add_f32_e32 v16, v16, v17
	global_store_dword v[18:19], v16, off
.LBB0_1181:
	s_or_b64 exec, exec, s[26:27]
	s_waitcnt vmcnt(7)
	v_lshlrev_b32_e32 v18, 16, v68
	v_and_b32_e32 v19, 0xffff0000, v68
	s_waitcnt lgkmcnt(0)
	v_lshlrev_b64 v[16:17], 10, v[88:89]
	v_lshlrev_b32_e32 v22, 16, v70
	v_and_b32_e32 v23, 0xffff0000, v70
	v_lshlrev_b32_e32 v24, 16, v71
	v_and_b32_e32 v25, 0xffff0000, v71
	v_pk_add_f32 v[12:13], v[12:13], v[18:19]
	v_lshlrev_b32_e32 v20, 16, v69
	v_and_b32_e32 v21, 0xffff0000, v69
	v_pk_add_f32 v[18:19], v[10:11], v[24:25]
	v_pk_add_f32 v[10:11], v[8:9], v[22:23]
	v_cvt_pk_bf16_f32 v8, v12, v13
	v_lshl_add_u64 v[12:13], v[16:17], 1, s[58:59]
	v_pk_add_f32 v[14:15], v[14:15], v[20:21]
	v_lshl_add_u64 v[12:13], v[178:179], 1, v[12:13]
	v_cvt_pk_bf16_f32 v9, v14, v15
	v_cvt_pk_bf16_f32 v10, v10, v11
	v_cvt_pk_bf16_f32 v11, v18, v19
	global_store_dwordx4 v[12:13], v[8:11], off nt
	v_lshlrev_b32_e32 v14, 16, v8
	v_lshlrev_b32_e32 v15, 16, v9
	v_and_b32_e32 v8, 0xffff0000, v8
	v_and_b32_e32 v9, 0xffff0000, v9
	v_mul_f32_e32 v8, v8, v8
	v_mul_f32_e32 v9, v9, v9
	v_lshlrev_b32_e32 v16, 16, v10
	v_and_b32_e32 v10, 0xffff0000, v10
	v_lshlrev_b32_e32 v17, 16, v11
	v_and_b32_e32 v11, 0xffff0000, v11
	v_fmac_f32_e32 v8, v14, v14
	v_fmac_f32_e32 v9, v15, v15
	v_add_f32_e32 v8, v8, v9
	v_mul_f32_e32 v9, v10, v10
	v_mul_f32_e32 v10, v11, v11
	s_waitcnt vmcnt(7)
	v_lshlrev_b32_e32 v26, 16, v64
	v_and_b32_e32 v27, 0xffff0000, v64
	v_lshlrev_b32_e32 v30, 16, v66
	v_and_b32_e32 v31, 0xffff0000, v66
	v_fmac_f32_e32 v9, v16, v16
	v_fmac_f32_e32 v10, v17, v17
	v_lshlrev_b32_e32 v28, 16, v65
	v_and_b32_e32 v29, 0xffff0000, v65
	v_lshlrev_b32_e32 v32, 16, v67
	v_and_b32_e32 v33, 0xffff0000, v67
	v_add_f32_e32 v9, v9, v10
	v_pk_add_f32 v[4:5], v[4:5], v[26:27]
	v_pk_add_f32 v[0:1], v[0:1], v[30:31]
	v_add_f32_e32 v10, v8, v9
	v_pk_add_f32 v[6:7], v[6:7], v[28:29]
	v_pk_add_f32 v[8:9], v[2:3], v[32:33]
	v_cvt_pk_bf16_f32 v2, v4, v5
	v_cvt_pk_bf16_f32 v3, v6, v7
	v_cvt_pk_bf16_f32 v4, v0, v1
	s_nop 0
	v_and_b32_e32 v1, 0xffff0000, v2
	v_lshlrev_b32_e32 v0, 16, v2
	v_and_b32_e32 v7, 0xffff0000, v3
	v_mul_f32_e32 v1, v1, v1
	v_lshlrev_b32_e32 v6, 16, v3
	v_fmac_f32_e32 v1, v0, v0
	v_mul_f32_e32 v0, v7, v7
	v_cvt_pk_bf16_f32 v5, v8, v9
	v_and_b32_e32 v9, 0xffff0000, v4
	v_and_b32_e32 v14, 0xffff0000, v5
	v_fmac_f32_e32 v0, v6, v6
	v_lshlrev_b32_e32 v8, 16, v4
	v_lshlrev_b32_e32 v11, 16, v5
	v_add_f32_e32 v0, v1, v0
	v_mul_f32_e32 v1, v9, v9
	v_mul_f32_e32 v6, v14, v14
	v_fmac_f32_e32 v1, v8, v8
	v_fmac_f32_e32 v6, v11, v11
	v_add_f32_e32 v1, v1, v6
	v_add_f32_e32 v0, v0, v1
	v_add_f32_e32 v0, v10, v0
	ds_bpermute_b32 v1, v112, v0
	global_store_dwordx4 v[12:13], v[2:5], off offset:256 nt
	s_waitcnt lgkmcnt(0)
	v_add_f32_e32 v0, v0, v1
	ds_bpermute_b32 v1, v113, v0
	s_and_saveexec_b64 s[26:27], s[36:37]
	s_cbranch_execz .LBB0_1183
	v_lshlrev_b64 v[2:3], 6, v[88:89]
	v_lshl_add_u64 v[2:3], s[62:63], 0, v[2:3]
	v_lshl_add_u64 v[2:3], s[24:25], 2, v[2:3]
	s_lshl_b32 s14, s35, 2
	v_lshl_add_u64 v[2:3], v[2:3], 0, s[14:15]
	s_waitcnt lgkmcnt(0)
	v_add_f32_e32 v0, v0, v1
	global_store_dword v[2:3], v0, off

.LBB0_1238:
	s_add_u32 s12, s88, s0
	s_waitcnt vmcnt(0)
	v_lshl_add_u64 v[14:15], s[88:89], 0, v[4:5]
	s_addc_u32 s13, s89, s1
	v_add_co_u32_e32 v38, vcc, s10, v14
	global_load_dwordx4 v[10:13], v[2:3], off
	s_nop 0
	v_addc_co_u32_e32 v39, vcc, 0, v15, vcc
	global_load_dwordx4 v[14:17], v0, s[12:13]
	global_load_dwordx4 v[18:21], v[38:39], off
	s_add_u32 s12, s12, 0x1f000000
	s_addc_u32 s13, s13, 0
	global_load_dwordx4 v[22:25], v1, s[12:13] offset:16
	global_load_dwordx4 v[26:29], v1, s[12:13] offset:32
	global_load_dwordx4 v[30:33], v1, s[12:13] offset:48
	global_load_dwordx4 v[34:37], v[2:3], off offset:16
	s_add_i32 s8, s8, s14
	s_add_u32 s0, s0, s2
	s_addc_u32 s1, s1, s3
	v_lshl_add_u64 v[4:5], v[4:5], 0, s[4:5]
	s_cmp_lt_i32 s8, 0x8000
	s_waitcnt vmcnt(5)
	v_mov_b32_e32 v40, v15
	v_mov_b32_e32 v41, v16
	v_mov_b32_e32 v15, v17
	v_pk_add_f32 v[14:15], v[40:41], v[14:15]
	s_waitcnt vmcnt(3)
	v_mov_b32_e32 v40, v23
	v_mov_b32_e32 v41, v24
	v_mov_b32_e32 v23, v25
	v_pk_add_f32 v[22:23], v[40:41], v[22:23]
	v_pk_add_f32 v[14:15], v[14:15], v[14:15] op_sel:[0,1] op_sel_hi:[1,0]
	v_pk_add_f32 v[22:23], v[22:23], v[22:23] op_sel:[0,1] op_sel_hi:[1,0]
	s_waitcnt vmcnt(2)
	v_add_f32_e32 v24, v26, v27
	v_add_f32_e32 v26, v28, v29
	s_waitcnt vmcnt(1)
	v_mov_b32_e32 v25, v32
	v_mov_b32_e32 v27, v33
	v_mov_b32_e32 v15, v30
	v_mov_b32_e32 v23, v31
	v_pk_add_f32 v[24:25], v[24:25], v[26:27]
	v_pk_add_f32 v[14:15], v[14:15], v[22:23]
	v_lshlrev_b32_e32 v16, 16, v18
	v_pk_add_f32 v[14:15], v[14:15], v[24:25]
	v_and_b32_e32 v17, 0xffff0000, v18
	v_add_f32_e32 v9, v14, v15
	v_fmamk_f32 v9, v9, 0x3a800000, v8
	v_mul_f32_e32 v14, 0x4b800000, v9
	v_cmp_gt_f32_e32 vcc, s9, v9
	v_lshlrev_b32_e32 v18, 16, v19
	v_and_b32_e32 v19, 0xffff0000, v19
	v_cndmask_b32_e32 v9, v9, v14, vcc
	v_rsq_f32_e32 v9, v9
	v_lshlrev_b32_e32 v42, 16, v20
	v_and_b32_e32 v43, 0xffff0000, v20
	v_lshlrev_b32_e32 v20, 16, v21
	v_mul_f32_e32 v14, 0x45800000, v9
	v_cndmask_b32_e32 v22, v9, v14, vcc
	v_and_b32_e32 v21, 0xffff0000, v21
	v_pk_mul_f32 v[14:15], v[22:23], v[16:17] op_sel_hi:[0,1]
	v_pk_mul_f32 v[16:17], v[22:23], v[18:19] op_sel_hi:[0,1]
	v_pk_mul_f32 v[18:19], v[22:23], v[42:43] op_sel_hi:[0,1]
	v_pk_mul_f32 v[20:21], v[22:23], v[20:21] op_sel_hi:[0,1]
	v_pk_mul_f32 v[10:11], v[10:11], v[14:15]
	v_pk_mul_f32 v[12:13], v[12:13], v[16:17]
	s_waitcnt vmcnt(0)
	v_pk_mul_f32 v[14:15], v[34:35], v[18:19]
	v_pk_mul_f32 v[16:17], v[36:37], v[20:21]
	global_store_dwordx4 v[6:7], v[10:13], off offset:-2064
	global_store_dwordx4 v[6:7], v[14:17], off offset:-2048
	global_load_dwordx4 v[10:13], v[38:39], off offset:1024
	s_nop 0
	global_load_dwordx4 v[14:17], v[2:3], off offset:2048
	global_load_dwordx4 v[18:21], v[2:3], off offset:2064
	s_waitcnt vmcnt(2)
	v_lshlrev_b32_e32 v24, 16, v10
	v_and_b32_e32 v25, 0xffff0000, v10
	v_lshlrev_b32_e32 v10, 16, v11
	v_and_b32_e32 v11, 0xffff0000, v11
	v_lshlrev_b32_e32 v26, 16, v12
	v_and_b32_e32 v27, 0xffff0000, v12
	v_lshlrev_b32_e32 v12, 16, v13
	v_and_b32_e32 v13, 0xffff0000, v13
	v_pk_mul_f32 v[24:25], v[22:23], v[24:25] op_sel_hi:[0,1]
	v_pk_mul_f32 v[28:29], v[22:23], v[10:11] op_sel_hi:[0,1]
	v_pk_mul_f32 v[26:27], v[22:23], v[26:27] op_sel_hi:[0,1]
	v_pk_mul_f32 v[22:23], v[22:23], v[12:13] op_sel_hi:[0,1]
	s_waitcnt vmcnt(1)
	v_pk_mul_f32 v[10:11], v[14:15], v[24:25]
	v_pk_mul_f32 v[12:13], v[16:17], v[28:29]
	s_waitcnt vmcnt(0)
	v_pk_mul_f32 v[14:15], v[18:19], v[26:27]
	v_pk_mul_f32 v[16:17], v[20:21], v[22:23]
	global_store_dwordx4 v[6:7], v[10:13], off offset:-16
	global_store_dwordx4 v[6:7], v[14:17], off nt
	v_lshl_add_u64 v[6:7], v[6:7], 0, s[6:7]
	s_cbranch_scc1 .LBB0_1238
